# GEMM K-loop issue-slot cleanup stack: 20 redundant lgkmcnt(0) waits deleted + 20 mid-block setprio toggle pairs removed, on top of P1 LDS tables + P2 pointer SALU
# speedup vs baseline: 1.0038x; 1.0019x over previous
; #define PG8_STAGE(bufoff, gbase, voff) do { _Pragma("unroll") for (int _i = 0; _i < 2; ++_i) \
;         __builtin_amdgcn_global_load_lds((const unsigned*)((const char*)(gbase) + (voff)[_i]), (PG8_LAS unsigned*)(lds + (bufoff) + ldsw + _i * 8192), 16, 0, 0); } while (0)
; #define PG8_LDA(dst, b, h) do { _Pragma("unroll") for (int m = 0; m < 4; ++m) _Pragma("unroll") for (int k = 0; k < 2; ++k) dst[m][k] = *(const PG8_LAS bf16x8*)(lds + PG8_SA(b, h) + aoff + m * 2048 + k * 1024); } while (0)
; #define PG8_LDB(dst, b, h) do { _Pragma("unroll") for (int n = 0; n < 2; ++n) _Pragma("unroll") for (int k = 0; k < 2; ++k) dst[n][k] = *(const PG8_LAS bf16x8*)(lds + PG8_SB(b, h) + boff + n * 2048 + k * 1024); } while (0)
; #define PG8_MMA(ai, bj, At, Bt) do { __builtin_amdgcn_s_setprio(1); _Pragma("unroll") for (int m = 0; m < 4; ++m) _Pragma("unroll") for (int n = 0; n < 2; ++n) _Pragma("unroll") for (int k = 0; k < 2; ++k) \
;         acc[ai][bj][m][n] = __builtin_amdgcn_mfma_f32_16x16x32_bf16(Bt[n][k], At[m][k], acc[ai][bj][m][n], 0, 0, 0); __builtin_amdgcn_s_setprio(0); } while (0)
; #define PG8_WAIT_V(n) asm volatile("s_waitcnt vmcnt(" #n ")" ::: "memory")
; #define PG8_WAIT_L(n) asm volatile("s_waitcnt lgkmcnt(" #n ")" ::: "memory")
; #define PG8_BAR __builtin_amdgcn_s_barrier()
; #define PG8_SCHED __builtin_amdgcn_sched_barrier(0)
; template <class Epi, class Sched, bool ALIGN_EPI = false, bool SP2 = false>
; __device__ __forceinline__ void gemm_phase(PG8_LAS unsigned char* lds, const Gemm g, const Sched& S, const Epi& E) {
;     ...
;             PG8_LDB(B0, 0, 0); PG8_LDB(B1, 0, 1); PG8_SCHED; PG8_LDA(At, 0, 0); PG8_STAGE(PG8_SA(1, 1), a1 + hstep, voffA);
;             PG8_WAIT_V(8); PG8_WAIT_L(0); PG8_BAR; PG8_MMA(0, 0, At, B0); PG8_MMA(0, 1, At, B1); PG8_BAR; PG8_SCHED;
;             PG8_LDA(At, 0, 1); PG8_STAGE(PG8_SB(0, 0), b2, voffB); PG8_STAGE(PG8_SB(0, 1), b2 + hstep, voffB); PG8_STAGE(PG8_SA(0, 0), a2, voffA);
;             PG8_WAIT_V(8); PG8_WAIT_L(0); PG8_BAR; PG8_MMA(1, 0, At, B0); PG8_MMA(1, 1, At, B1); PG8_BAR; PG8_SCHED;
.LBB0_246:
	ds_read_b128 v[130:133], v201
	ds_read_b128 v[134:137], v201 offset:1024
	ds_read_b128 v[176:179], v201 offset:2048
	ds_read_b128 v[180:183], v201 offset:3072
	ds_read_b128 v[184:187], v202
	ds_read_b128 v[188:191], v202 offset:1024
	ds_read_b128 v[192:195], v202 offset:2048
	ds_read_b128 v[210:213], v202 offset:3072
	s_add_u32 s0, s28, 0xfffc0080
	s_addc_u32 s1, s29, -1
	s_cmp_eq_u32 s76, 12
	s_cselect_b32 s35, s21, s1
	s_cselect_b32 s34, vcc_lo, s0
	s_cselect_b32 s31, s19, s73
	s_cselect_b32 s30, vcc_hi, s72
	v_lshl_add_u64 v[196:197], s[28:29], 0, v[170:171]
	s_add_i32 m0, s41, 0xc000
	ds_read_b128 v[214:217], v198
	ds_read_b128 v[218:221], v198 offset:1024
	ds_read_b128 v[222:225], v198 offset:2048
	ds_read_b128 v[226:229], v198 offset:3072
	ds_read_b128 v[230:233], v198 offset:4096
	ds_read_b128 v[234:237], v198 offset:5120
	ds_read_b128 v[238:241], v198 offset:6144
	ds_read_b128 v[242:245], v198 offset:7168
	global_load_lds_dwordx4 v[196:197], off
	v_lshl_add_u64 v[196:197], s[28:29], 0, v[172:173]
	s_add_i32 m0, s41, 0xe000
	s_nop 0
	global_load_lds_dwordx4 v[196:197], off
	s_waitcnt vmcnt(8)
	s_waitcnt lgkmcnt(0)
	s_barrier
	s_setprio 1
	v_mfma_f32_16x16x32_bf16 v[126:129], v[130:133], v[214:217], v[126:129]
	v_mfma_f32_16x16x32_bf16 v[122:125], v[176:179], v[214:217], v[122:125]
	v_mfma_f32_16x16x32_bf16 v[114:117], v[130:133], v[222:225], v[114:117]
	v_mfma_f32_16x16x32_bf16 v[106:109], v[176:179], v[222:225], v[106:109]
	v_mfma_f32_16x16x32_bf16 v[102:105], v[130:133], v[230:233], v[102:105]
	v_mfma_f32_16x16x32_bf16 v[94:97], v[176:179], v[230:233], v[94:97]
	v_mfma_f32_16x16x32_bf16 v[86:89], v[130:133], v[238:241], v[86:89]
	v_mfma_f32_16x16x32_bf16 v[78:81], v[176:179], v[238:241], v[78:81]
	v_mfma_f32_16x16x32_bf16 v[126:129], v[134:137], v[218:221], v[126:129]
	v_mfma_f32_16x16x32_bf16 v[122:125], v[180:183], v[218:221], v[122:125]
	v_mfma_f32_16x16x32_bf16 v[114:117], v[134:137], v[226:229], v[114:117]
	v_mfma_f32_16x16x32_bf16 v[106:109], v[180:183], v[226:229], v[106:109]
	v_mfma_f32_16x16x32_bf16 v[102:105], v[134:137], v[234:237], v[102:105]
	v_mfma_f32_16x16x32_bf16 v[94:97], v[180:183], v[234:237], v[94:97]
	v_mfma_f32_16x16x32_bf16 v[86:89], v[134:137], v[242:245], v[86:89]
	v_mfma_f32_16x16x32_bf16 v[78:81], v[180:183], v[242:245], v[78:81]
	v_mfma_f32_16x16x32_bf16 v[118:121], v[184:187], v[214:217], v[118:121]
	v_mfma_f32_16x16x32_bf16 v[110:113], v[192:195], v[214:217], v[110:113]
	v_mfma_f32_16x16x32_bf16 v[98:101], v[184:187], v[222:225], v[98:101]
	v_mfma_f32_16x16x32_bf16 v[90:93], v[192:195], v[222:225], v[90:93]
	v_mfma_f32_16x16x32_bf16 v[82:85], v[184:187], v[230:233], v[82:85]
	v_mfma_f32_16x16x32_bf16 v[74:77], v[192:195], v[230:233], v[74:77]
	v_mfma_f32_16x16x32_bf16 v[70:73], v[184:187], v[238:241], v[70:73]
	v_mfma_f32_16x16x32_bf16 v[66:69], v[192:195], v[238:241], v[66:69]
	v_mfma_f32_16x16x32_bf16 v[118:121], v[188:191], v[218:221], v[118:121]
	v_mfma_f32_16x16x32_bf16 v[110:113], v[210:213], v[218:221], v[110:113]
	v_mfma_f32_16x16x32_bf16 v[98:101], v[188:191], v[226:229], v[98:101]
	v_mfma_f32_16x16x32_bf16 v[90:93], v[210:213], v[226:229], v[90:93]
	v_mfma_f32_16x16x32_bf16 v[82:85], v[188:191], v[234:237], v[82:85]
	v_mfma_f32_16x16x32_bf16 v[74:77], v[210:213], v[234:237], v[74:77]
	v_mfma_f32_16x16x32_bf16 v[70:73], v[188:191], v[242:245], v[70:73]
	v_mfma_f32_16x16x32_bf16 v[66:69], v[210:213], v[242:245], v[66:69]
	s_setprio 0
	s_barrier
	s_add_i32 s0, s92, s38
	v_lshl_add_u64 v[196:197], s[30:31], 0, v[142:143]
	s_mov_b32 m0, s0
	ds_read_b128 v[214:217], v198 offset:16384
	ds_read_b128 v[218:221], v198 offset:17408
	ds_read_b128 v[222:225], v198 offset:18432
	ds_read_b128 v[226:229], v198 offset:19456
	ds_read_b128 v[230:233], v198 offset:20480
	ds_read_b128 v[234:237], v198 offset:21504
	ds_read_b128 v[238:241], v198 offset:22528
	ds_read_b128 v[242:245], v198 offset:23552
	global_load_lds_dwordx4 v[196:197], off
	s_add_i32 m0, s0, 0x2000
	s_add_u32 s0, s30, 0x40000
	v_lshl_add_u64 v[246:247], s[30:31], 0, v[138:139]
	s_addc_u32 s1, s31, 0
	s_add_i32 s77, s93, s38
	global_load_lds_dwordx4 v[246:247], off
	v_lshl_add_u64 v[248:249], s[0:1], 0, v[142:143]
	s_mov_b32 m0, s77
	v_lshl_add_u64 v[250:251], s[34:35], 0, v[140:141]
	global_load_lds_dwordx4 v[248:249], off
	v_lshl_add_u64 v[248:249], s[0:1], 0, v[138:139]
	s_add_i32 m0, s77, 0x2000
	s_nop 0
	global_load_lds_dwordx4 v[248:249], off
	v_lshl_add_u64 v[248:249], s[34:35], 0, v[144:145]
	s_mov_b32 m0, s41
	s_nop 0
	global_load_lds_dwordx4 v[248:249], off
	s_mov_b32 m0, s69
	s_nop 0
	global_load_lds_dwordx4 v[250:251], off
	s_waitcnt vmcnt(8)
	s_waitcnt lgkmcnt(0)
	s_barrier
; #define PG8_STAGE(bufoff, gbase, voff) do { _Pragma("unroll") for (int _i = 0; _i < 2; ++_i) \
;         __builtin_amdgcn_global_load_lds((const unsigned*)((const char*)(gbase) + (voff)[_i]), (PG8_LAS unsigned*)(lds + (bufoff) + ldsw + _i * 8192), 16, 0, 0); } while (0)
; #define PG8_LDA(dst, b, h) do { _Pragma("unroll") for (int m = 0; m < 4; ++m) _Pragma("unroll") for (int k = 0; k < 2; ++k) dst[m][k] = *(const PG8_LAS bf16x8*)(lds + PG8_SA(b, h) + aoff + m * 2048 + k * 1024); } while (0)
; #define PG8_LDB(dst, b, h) do { _Pragma("unroll") for (int n = 0; n < 2; ++n) _Pragma("unroll") for (int k = 0; k < 2; ++k) dst[n][k] = *(const PG8_LAS bf16x8*)(lds + PG8_SB(b, h) + boff + n * 2048 + k * 1024); } while (0)
; #define PG8_MMA(ai, bj, At, Bt) do { __builtin_amdgcn_s_setprio(1); _Pragma("unroll") for (int m = 0; m < 4; ++m) _Pragma("unroll") for (int n = 0; n < 2; ++n) _Pragma("unroll") for (int k = 0; k < 2; ++k) \
;         acc[ai][bj][m][n] = __builtin_amdgcn_mfma_f32_16x16x32_bf16(Bt[n][k], At[m][k], acc[ai][bj][m][n], 0, 0, 0); __builtin_amdgcn_s_setprio(0); } while (0)
; #define PG8_WAIT_V(n) asm volatile("s_waitcnt vmcnt(" #n ")" ::: "memory")
; #define PG8_WAIT_L(n) asm volatile("s_waitcnt lgkmcnt(" #n ")" ::: "memory")
; #define PG8_BAR __builtin_amdgcn_s_barrier()
; #define PG8_SCHED __builtin_amdgcn_sched_barrier(0)
; template <class Epi, class Sched, bool ALIGN_EPI = false, bool SP2 = false>
; __device__ __forceinline__ void gemm_phase(PG8_LAS unsigned char* lds, const Gemm g, const Sched& S, const Epi& E) {
;     ...
;             PG8_WAIT_V(8); PG8_WAIT_L(0); PG8_BAR; PG8_MMA(1, 0, At, B0); PG8_MMA(1, 1, At, B1); PG8_BAR; PG8_SCHED;
;             PG8_LDB(B0, 1, 0); PG8_LDB(B1, 1, 1); PG8_SCHED; PG8_LDA(At, 1, 0); PG8_STAGE(PG8_SA(0, 1), a2 + hstep, voffA);
;             PG8_WAIT_V(8); PG8_WAIT_L(0); PG8_BAR; PG8_MMA(0, 0, At, B0); PG8_MMA(0, 1, At, B1); PG8_BAR; PG8_SCHED;
	s_setprio 1
	v_mfma_f32_16x16x32_bf16 v[62:65], v[130:133], v[214:217], v[62:65]
	v_mfma_f32_16x16x32_bf16 v[58:61], v[176:179], v[214:217], v[58:61]
	v_mfma_f32_16x16x32_bf16 v[54:57], v[130:133], v[222:225], v[54:57]
	v_mfma_f32_16x16x32_bf16 v[46:49], v[176:179], v[222:225], v[46:49]
	v_mfma_f32_16x16x32_bf16 v[38:41], v[130:133], v[230:233], v[38:41]
	v_mfma_f32_16x16x32_bf16 v[30:33], v[176:179], v[230:233], v[30:33]
	v_mfma_f32_16x16x32_bf16 v[22:25], v[130:133], v[238:241], v[22:25]
	v_mfma_f32_16x16x32_bf16 v[14:17], v[176:179], v[238:241], v[14:17]
	v_mfma_f32_16x16x32_bf16 v[62:65], v[134:137], v[218:221], v[62:65]
	v_mfma_f32_16x16x32_bf16 v[58:61], v[180:183], v[218:221], v[58:61]
	v_mfma_f32_16x16x32_bf16 v[54:57], v[134:137], v[226:229], v[54:57]
	v_mfma_f32_16x16x32_bf16 v[46:49], v[180:183], v[226:229], v[46:49]
	v_mfma_f32_16x16x32_bf16 v[38:41], v[134:137], v[234:237], v[38:41]
	v_mfma_f32_16x16x32_bf16 v[30:33], v[180:183], v[234:237], v[30:33]
	v_mfma_f32_16x16x32_bf16 v[22:25], v[134:137], v[242:245], v[22:25]
	v_mfma_f32_16x16x32_bf16 v[14:17], v[180:183], v[242:245], v[14:17]
	v_mfma_f32_16x16x32_bf16 v[50:53], v[184:187], v[214:217], v[50:53]
	v_mfma_f32_16x16x32_bf16 v[42:45], v[192:195], v[214:217], v[42:45]
	v_mfma_f32_16x16x32_bf16 v[34:37], v[184:187], v[222:225], v[34:37]
	v_mfma_f32_16x16x32_bf16 v[26:29], v[192:195], v[222:225], v[26:29]
	v_mfma_f32_16x16x32_bf16 v[18:21], v[184:187], v[230:233], v[18:21]
	v_mfma_f32_16x16x32_bf16 v[10:13], v[192:195], v[230:233], v[10:13]
	v_mfma_f32_16x16x32_bf16 v[6:9], v[184:187], v[238:241], v[6:9]
	v_mfma_f32_16x16x32_bf16 v[2:5], v[192:195], v[238:241], v[2:5]
	v_mfma_f32_16x16x32_bf16 v[50:53], v[188:191], v[218:221], v[50:53]
	v_mfma_f32_16x16x32_bf16 v[42:45], v[210:213], v[218:221], v[42:45]
	v_mfma_f32_16x16x32_bf16 v[34:37], v[188:191], v[226:229], v[34:37]
	v_mfma_f32_16x16x32_bf16 v[26:29], v[210:213], v[226:229], v[26:29]
	v_mfma_f32_16x16x32_bf16 v[18:21], v[188:191], v[234:237], v[18:21]
	v_mfma_f32_16x16x32_bf16 v[10:13], v[210:213], v[234:237], v[10:13]
	v_mfma_f32_16x16x32_bf16 v[6:9], v[188:191], v[242:245], v[6:9]
	v_mfma_f32_16x16x32_bf16 v[2:5], v[210:213], v[242:245], v[2:5]
	s_setprio 0
	s_barrier
	ds_read_b128 v[130:133], v203
	ds_read_b128 v[134:137], v203 offset:1024
	ds_read_b128 v[176:179], v203 offset:2048
	ds_read_b128 v[180:183], v203 offset:3072
	ds_read_b128 v[184:187], v204
	ds_read_b128 v[188:191], v204 offset:1024
	ds_read_b128 v[192:195], v204 offset:2048
	ds_read_b128 v[210:213], v204 offset:3072
	s_add_u32 s0, s34, 0x40000
	s_addc_u32 s1, s35, 0
	s_mov_b32 m0, s82
	v_lshl_add_u64 v[252:253], s[0:1], 0, v[144:145]
	ds_read_b128 v[214:217], v198 offset:32768
	ds_read_b128 v[218:221], v198 offset:33792
	ds_read_b128 v[222:225], v198 offset:34816
	ds_read_b128 v[226:229], v198 offset:35840
	ds_read_b128 v[230:233], v198 offset:36864
	ds_read_b128 v[234:237], v198 offset:37888
	ds_read_b128 v[238:241], v198 offset:38912
	ds_read_b128 v[242:245], v198 offset:39936
	global_load_lds_dwordx4 v[252:253], off
	v_lshl_add_u64 v[252:253], s[0:1], 0, v[140:141]
	s_mov_b32 m0, s83
	s_nop 0
	global_load_lds_dwordx4 v[252:253], off
	s_waitcnt vmcnt(8)
	s_waitcnt lgkmcnt(0)
	s_barrier
	s_setprio 1
	v_mfma_f32_16x16x32_bf16 v[126:129], v[130:133], v[214:217], v[126:129]
	v_mfma_f32_16x16x32_bf16 v[122:125], v[176:179], v[214:217], v[122:125]
	v_mfma_f32_16x16x32_bf16 v[114:117], v[130:133], v[222:225], v[114:117]
	v_mfma_f32_16x16x32_bf16 v[106:109], v[176:179], v[222:225], v[106:109]
	v_mfma_f32_16x16x32_bf16 v[102:105], v[130:133], v[230:233], v[102:105]
	v_mfma_f32_16x16x32_bf16 v[94:97], v[176:179], v[230:233], v[94:97]
	v_mfma_f32_16x16x32_bf16 v[86:89], v[130:133], v[238:241], v[86:89]
	v_mfma_f32_16x16x32_bf16 v[78:81], v[176:179], v[238:241], v[78:81]
	v_mfma_f32_16x16x32_bf16 v[126:129], v[134:137], v[218:221], v[126:129]
	v_mfma_f32_16x16x32_bf16 v[122:125], v[180:183], v[218:221], v[122:125]
	v_mfma_f32_16x16x32_bf16 v[114:117], v[134:137], v[226:229], v[114:117]
	v_mfma_f32_16x16x32_bf16 v[106:109], v[180:183], v[226:229], v[106:109]
	v_mfma_f32_16x16x32_bf16 v[102:105], v[134:137], v[234:237], v[102:105]
	v_mfma_f32_16x16x32_bf16 v[94:97], v[180:183], v[234:237], v[94:97]
	v_mfma_f32_16x16x32_bf16 v[86:89], v[134:137], v[242:245], v[86:89]
	v_mfma_f32_16x16x32_bf16 v[78:81], v[180:183], v[242:245], v[78:81]
	v_mfma_f32_16x16x32_bf16 v[118:121], v[184:187], v[214:217], v[118:121]
	v_mfma_f32_16x16x32_bf16 v[110:113], v[192:195], v[214:217], v[110:113]
	v_mfma_f32_16x16x32_bf16 v[98:101], v[184:187], v[222:225], v[98:101]
	v_mfma_f32_16x16x32_bf16 v[90:93], v[192:195], v[222:225], v[90:93]
	v_mfma_f32_16x16x32_bf16 v[82:85], v[184:187], v[230:233], v[82:85]
	v_mfma_f32_16x16x32_bf16 v[74:77], v[192:195], v[230:233], v[74:77]
	v_mfma_f32_16x16x32_bf16 v[70:73], v[184:187], v[238:241], v[70:73]
	v_mfma_f32_16x16x32_bf16 v[66:69], v[192:195], v[238:241], v[66:69]
	v_mfma_f32_16x16x32_bf16 v[118:121], v[188:191], v[218:221], v[118:121]
	v_mfma_f32_16x16x32_bf16 v[110:113], v[210:213], v[218:221], v[110:113]
	v_mfma_f32_16x16x32_bf16 v[98:101], v[188:191], v[226:229], v[98:101]
	v_mfma_f32_16x16x32_bf16 v[90:93], v[210:213], v[226:229], v[90:93]
	v_mfma_f32_16x16x32_bf16 v[82:85], v[188:191], v[234:237], v[82:85]
	v_mfma_f32_16x16x32_bf16 v[74:77], v[210:213], v[234:237], v[74:77]
	v_mfma_f32_16x16x32_bf16 v[70:73], v[188:191], v[242:245], v[70:73]
	v_mfma_f32_16x16x32_bf16 v[66:69], v[210:213], v[242:245], v[66:69]
	s_setprio 0
	s_barrier
; #define PG8_STAGE(bufoff, gbase, voff) do { _Pragma("unroll") for (int _i = 0; _i < 2; ++_i) \
;         __builtin_amdgcn_global_load_lds((const unsigned*)((const char*)(gbase) + (voff)[_i]), (PG8_LAS unsigned*)(lds + (bufoff) + ldsw + _i * 8192), 16, 0, 0); } while (0)
; #define PG8_LDA(dst, b, h) do { _Pragma("unroll") for (int m = 0; m < 4; ++m) _Pragma("unroll") for (int k = 0; k < 2; ++k) dst[m][k] = *(const PG8_LAS bf16x8*)(lds + PG8_SA(b, h) + aoff + m * 2048 + k * 1024); } while (0)
; #define PG8_MMA(ai, bj, At, Bt) do { __builtin_amdgcn_s_setprio(1); _Pragma("unroll") for (int m = 0; m < 4; ++m) _Pragma("unroll") for (int n = 0; n < 2; ++n) _Pragma("unroll") for (int k = 0; k < 2; ++k) \
;         acc[ai][bj][m][n] = __builtin_amdgcn_mfma_f32_16x16x32_bf16(Bt[n][k], At[m][k], acc[ai][bj][m][n], 0, 0, 0); __builtin_amdgcn_s_setprio(0); } while (0)
; #define PG8_WAIT_V(n) asm volatile("s_waitcnt vmcnt(" #n ")" ::: "memory")
; #define PG8_WAIT_L(n) asm volatile("s_waitcnt lgkmcnt(" #n ")" ::: "memory")
; #define PG8_BAR __builtin_amdgcn_s_barrier()
; #define PG8_SCHED __builtin_amdgcn_sched_barrier(0)
; template <class Epi, class Sched, bool ALIGN_EPI = false, bool SP2 = false>
; __device__ __forceinline__ void gemm_phase(PG8_LAS unsigned char* lds, const Gemm g, const Sched& S, const Epi& E) {
;     ...
;             PG8_LDA(At, 1, 1); PG8_STAGE(PG8_SB(1, 0), b3, voffB); PG8_STAGE(PG8_SB(1, 1), b3 + hstep, voffB); PG8_STAGE(PG8_SA(1, 0), a3, voffA);
;             PG8_WAIT_V(8); PG8_WAIT_L(0); PG8_BAR; PG8_MMA(1, 0, At, B0); PG8_MMA(1, 1, At, B1); PG8_BAR; PG8_SCHED;
	s_add_i32 s0, s94, s38
	v_lshl_add_u64 v[196:197], v[196:197], 0, s[6:7]
	s_mov_b32 m0, s0
	ds_read_b128 v[214:217], v198 offset:49152
	ds_read_b128 v[218:221], v198 offset:50176
	ds_read_b128 v[222:225], v198 offset:51200
	ds_read_b128 v[226:229], v198 offset:52224
	ds_read_b128 v[230:233], v198 offset:53248
	ds_read_b128 v[234:237], v198 offset:54272
	ds_read_b128 v[238:241], v198 offset:55296
	ds_read_b128 v[242:245], v198 offset:56320
	global_load_lds_dwordx4 v[196:197], off
	s_add_i32 m0, s0, 0x2000
	s_add_u32 s0, s30, 0x40080
	v_lshl_add_u64 v[196:197], v[246:247], 0, s[6:7]
	s_addc_u32 s1, s31, 0
	s_add_i32 s30, s95, s38
	global_load_lds_dwordx4 v[196:197], off
	v_lshl_add_u64 v[196:197], s[0:1], 0, v[142:143]
	s_mov_b32 m0, s30
	s_nop 0
	global_load_lds_dwordx4 v[196:197], off
	v_lshl_add_u64 v[196:197], s[0:1], 0, v[138:139]
	s_add_i32 m0, s30, 0x2000
	s_nop 0
	global_load_lds_dwordx4 v[196:197], off
	v_lshl_add_u64 v[196:197], v[248:249], 0, s[6:7]
	s_mov_b32 m0, s85
	s_nop 0
	global_load_lds_dwordx4 v[196:197], off
	v_lshl_add_u64 v[196:197], v[250:251], 0, s[6:7]
	s_mov_b32 m0, s89
	s_nop 0
	global_load_lds_dwordx4 v[196:197], off
	s_waitcnt vmcnt(8)
	s_waitcnt lgkmcnt(0)
	s_barrier
	s_setprio 1
	v_mfma_f32_16x16x32_bf16 v[62:65], v[130:133], v[214:217], v[62:65]
	v_mfma_f32_16x16x32_bf16 v[58:61], v[176:179], v[214:217], v[58:61]
	v_mfma_f32_16x16x32_bf16 v[54:57], v[130:133], v[222:225], v[54:57]
	v_mfma_f32_16x16x32_bf16 v[46:49], v[176:179], v[222:225], v[46:49]
	v_mfma_f32_16x16x32_bf16 v[38:41], v[130:133], v[230:233], v[38:41]
	v_mfma_f32_16x16x32_bf16 v[30:33], v[176:179], v[230:233], v[30:33]
	v_mfma_f32_16x16x32_bf16 v[22:25], v[130:133], v[238:241], v[22:25]
	v_mfma_f32_16x16x32_bf16 v[14:17], v[176:179], v[238:241], v[14:17]
	v_mfma_f32_16x16x32_bf16 v[62:65], v[134:137], v[218:221], v[62:65]
	v_mfma_f32_16x16x32_bf16 v[58:61], v[180:183], v[218:221], v[58:61]
	v_mfma_f32_16x16x32_bf16 v[54:57], v[134:137], v[226:229], v[54:57]
	v_mfma_f32_16x16x32_bf16 v[46:49], v[180:183], v[226:229], v[46:49]
	v_mfma_f32_16x16x32_bf16 v[38:41], v[134:137], v[234:237], v[38:41]
	v_mfma_f32_16x16x32_bf16 v[30:33], v[180:183], v[234:237], v[30:33]
	v_mfma_f32_16x16x32_bf16 v[22:25], v[134:137], v[242:245], v[22:25]
	v_mfma_f32_16x16x32_bf16 v[14:17], v[180:183], v[242:245], v[14:17]
	v_mfma_f32_16x16x32_bf16 v[50:53], v[184:187], v[214:217], v[50:53]
	v_mfma_f32_16x16x32_bf16 v[42:45], v[192:195], v[214:217], v[42:45]
	v_mfma_f32_16x16x32_bf16 v[34:37], v[184:187], v[222:225], v[34:37]
	v_mfma_f32_16x16x32_bf16 v[26:29], v[192:195], v[222:225], v[26:29]
	v_mfma_f32_16x16x32_bf16 v[18:21], v[184:187], v[230:233], v[18:21]
	v_mfma_f32_16x16x32_bf16 v[10:13], v[192:195], v[230:233], v[10:13]
	v_mfma_f32_16x16x32_bf16 v[6:9], v[184:187], v[238:241], v[6:9]
	v_mfma_f32_16x16x32_bf16 v[2:5], v[192:195], v[238:241], v[2:5]
	v_mfma_f32_16x16x32_bf16 v[50:53], v[188:191], v[218:221], v[50:53]
	v_mfma_f32_16x16x32_bf16 v[42:45], v[210:213], v[218:221], v[42:45]
	v_mfma_f32_16x16x32_bf16 v[34:37], v[188:191], v[226:229], v[34:37]
	v_mfma_f32_16x16x32_bf16 v[26:29], v[210:213], v[226:229], v[26:29]
	v_mfma_f32_16x16x32_bf16 v[18:21], v[188:191], v[234:237], v[18:21]
	v_mfma_f32_16x16x32_bf16 v[10:13], v[210:213], v[234:237], v[10:13]
	v_mfma_f32_16x16x32_bf16 v[6:9], v[188:191], v[242:245], v[6:9]
	v_mfma_f32_16x16x32_bf16 v[2:5], v[210:213], v[242:245], v[2:5]
	s_setprio 0
	s_barrier
	s_add_i32 s76, s76, 2
	s_add_u32 s28, s28, 0x100
	s_addc_u32 s29, s29, 0
	s_add_u32 s72, s72, 0x100
	s_addc_u32 s73, s73, 0
	s_cmp_gt_u32 s76, 13
	s_cbranch_scc0 .LBB0_246
	s_and_b64 vcc, exec, s[8:9]
	s_cbranch_vccz .LBB0_249
	s_barrier

; #define PG8_STAGE(bufoff, gbase, voff) do { _Pragma("unroll") for (int _i = 0; _i < 2; ++_i) \
;         __builtin_amdgcn_global_load_lds((const unsigned*)((const char*)(gbase) + (voff)[_i]), (PG8_LAS unsigned*)(lds + (bufoff) + ldsw + _i * 8192), 16, 0, 0); } while (0)
; #define PG8_LDA(dst, b, h) do { _Pragma("unroll") for (int m = 0; m < 4; ++m) _Pragma("unroll") for (int k = 0; k < 2; ++k) dst[m][k] = *(const PG8_LAS bf16x8*)(lds + PG8_SA(b, h) + aoff + m * 2048 + k * 1024); } while (0)
; #define PG8_LDB(dst, b, h) do { _Pragma("unroll") for (int n = 0; n < 2; ++n) _Pragma("unroll") for (int k = 0; k < 2; ++k) dst[n][k] = *(const PG8_LAS bf16x8*)(lds + PG8_SB(b, h) + boff + n * 2048 + k * 1024); } while (0)
; #define PG8_MMA(ai, bj, At, Bt) do { __builtin_amdgcn_s_setprio(1); _Pragma("unroll") for (int m = 0; m < 4; ++m) _Pragma("unroll") for (int n = 0; n < 2; ++n) _Pragma("unroll") for (int k = 0; k < 2; ++k) \
;         acc[ai][bj][m][n] = __builtin_amdgcn_mfma_f32_16x16x32_bf16(Bt[n][k], At[m][k], acc[ai][bj][m][n], 0, 0, 0); __builtin_amdgcn_s_setprio(0); } while (0)
; #define PG8_WAIT_V(n) asm volatile("s_waitcnt vmcnt(" #n ")" ::: "memory")
; #define PG8_WAIT_L(n) asm volatile("s_waitcnt lgkmcnt(" #n ")" ::: "memory")
; #define PG8_BAR __builtin_amdgcn_s_barrier()
; #define PG8_SCHED __builtin_amdgcn_sched_barrier(0)
; template <class Epi, class Sched, bool ALIGN_EPI = false, bool SP2 = false>
; __device__ __forceinline__ void gemm_phase(PG8_LAS unsigned char* lds, const Gemm g, const Sched& S, const Epi& E) {
;     ...
;             PG8_LDB(B0, 0, 0); PG8_LDB(B1, 0, 1); PG8_SCHED; PG8_LDA(At, 0, 0); PG8_STAGE(PG8_SA(1, 1), a1 + hstep, voffA);
;             PG8_WAIT_V(8); PG8_WAIT_L(0); PG8_BAR; PG8_MMA(0, 0, At, B0); PG8_MMA(0, 1, At, B1); PG8_BAR; PG8_SCHED;
;             PG8_LDA(At, 0, 1); PG8_STAGE(PG8_SB(0, 0), b2, voffB); PG8_STAGE(PG8_SB(0, 1), b2 + hstep, voffB); PG8_STAGE(PG8_SA(0, 0), a2, voffA);
;             PG8_WAIT_V(8); PG8_WAIT_L(0); PG8_BAR; PG8_MMA(1, 0, At, B0); PG8_MMA(1, 1, At, B1); PG8_BAR; PG8_SCHED;
.LBB0_1230:
	ds_read_b128 v[144:147], v166
	ds_read_b128 v[148:151], v166 offset:1024
	ds_read_b128 v[152:155], v166 offset:2048
	ds_read_b128 v[172:175], v166 offset:3072
	ds_read_b128 v[176:179], v167
	ds_read_b128 v[180:183], v167 offset:1024
	ds_read_b128 v[184:187], v167 offset:2048
	ds_read_b128 v[188:191], v167 offset:3072
	s_add_u32 s0, s30, 0xfffc0080
	s_addc_u32 s1, s31, -1
	s_cmp_eq_u32 s76, 12
	s_cselect_b32 s37, s21, s1
	s_cselect_b32 s36, s29, s0
	s_cselect_b32 s35, s19, s73
	s_cselect_b32 s34, s84, s72
	v_lshl_add_u64 v[226:227], s[30:31], 0, v[138:139]
	s_add_i32 m0, s40, 0xc000
	ds_read_b128 v[192:195], v168
	ds_read_b128 v[196:199], v168 offset:1024
	ds_read_b128 v[200:203], v168 offset:2048
	ds_read_b128 v[204:207], v168 offset:3072
	ds_read_b128 v[210:213], v168 offset:4096
	ds_read_b128 v[214:217], v168 offset:5120
	ds_read_b128 v[218:221], v168 offset:6144
	ds_read_b128 v[222:225], v168 offset:7168
	global_load_lds_dwordx4 v[226:227], off
	v_lshl_add_u64 v[226:227], s[30:31], 0, v[140:141]
	s_add_i32 m0, s40, 0xe000
	s_nop 0
	global_load_lds_dwordx4 v[226:227], off
	s_waitcnt vmcnt(8)
	s_waitcnt lgkmcnt(0)
	s_barrier
	s_setprio 1
	v_mfma_f32_16x16x32_bf16 v[126:129], v[144:147], v[192:195], v[126:129]
	v_mfma_f32_16x16x32_bf16 v[122:125], v[152:155], v[192:195], v[122:125]
	v_mfma_f32_16x16x32_bf16 v[110:113], v[144:147], v[200:203], v[110:113]
	v_mfma_f32_16x16x32_bf16 v[106:109], v[152:155], v[200:203], v[106:109]
	v_mfma_f32_16x16x32_bf16 v[94:97], v[144:147], v[210:213], v[94:97]
	v_mfma_f32_16x16x32_bf16 v[90:93], v[152:155], v[210:213], v[90:93]
	v_mfma_f32_16x16x32_bf16 v[78:81], v[144:147], v[218:221], v[78:81]
	v_mfma_f32_16x16x32_bf16 v[74:77], v[152:155], v[218:221], v[74:77]
	v_mfma_f32_16x16x32_bf16 v[126:129], v[148:151], v[196:199], v[126:129]
	v_mfma_f32_16x16x32_bf16 v[122:125], v[172:175], v[196:199], v[122:125]
	v_mfma_f32_16x16x32_bf16 v[110:113], v[148:151], v[204:207], v[110:113]
	v_mfma_f32_16x16x32_bf16 v[106:109], v[172:175], v[204:207], v[106:109]
	v_mfma_f32_16x16x32_bf16 v[94:97], v[148:151], v[214:217], v[94:97]
	v_mfma_f32_16x16x32_bf16 v[90:93], v[172:175], v[214:217], v[90:93]
	v_mfma_f32_16x16x32_bf16 v[78:81], v[148:151], v[222:225], v[78:81]
	v_mfma_f32_16x16x32_bf16 v[74:77], v[172:175], v[222:225], v[74:77]
	v_mfma_f32_16x16x32_bf16 v[118:121], v[176:179], v[192:195], v[118:121]
	v_mfma_f32_16x16x32_bf16 v[114:117], v[184:187], v[192:195], v[114:117]
	v_mfma_f32_16x16x32_bf16 v[102:105], v[176:179], v[200:203], v[102:105]
	v_mfma_f32_16x16x32_bf16 v[98:101], v[184:187], v[200:203], v[98:101]
	v_mfma_f32_16x16x32_bf16 v[86:89], v[176:179], v[210:213], v[86:89]
	v_mfma_f32_16x16x32_bf16 v[82:85], v[184:187], v[210:213], v[82:85]
	v_mfma_f32_16x16x32_bf16 v[70:73], v[176:179], v[218:221], v[70:73]
	v_mfma_f32_16x16x32_bf16 v[66:69], v[184:187], v[218:221], v[66:69]
	v_mfma_f32_16x16x32_bf16 v[118:121], v[180:183], v[196:199], v[118:121]
	v_mfma_f32_16x16x32_bf16 v[114:117], v[188:191], v[196:199], v[114:117]
	v_mfma_f32_16x16x32_bf16 v[102:105], v[180:183], v[204:207], v[102:105]
	v_mfma_f32_16x16x32_bf16 v[98:101], v[188:191], v[204:207], v[98:101]
	v_mfma_f32_16x16x32_bf16 v[86:89], v[180:183], v[214:217], v[86:89]
	v_mfma_f32_16x16x32_bf16 v[82:85], v[188:191], v[214:217], v[82:85]
	v_mfma_f32_16x16x32_bf16 v[70:73], v[180:183], v[222:225], v[70:73]
	v_mfma_f32_16x16x32_bf16 v[66:69], v[188:191], v[222:225], v[66:69]
	s_setprio 0
	s_barrier
	s_add_i32 s0, s58, s39
	v_lshl_add_u64 v[226:227], s[34:35], 0, v[132:133]
	s_mov_b32 m0, s0
	ds_read_b128 v[192:195], v168 offset:16384
	ds_read_b128 v[196:199], v168 offset:17408
	ds_read_b128 v[200:203], v168 offset:18432
	ds_read_b128 v[204:207], v168 offset:19456
	ds_read_b128 v[210:213], v168 offset:20480
	ds_read_b128 v[214:217], v168 offset:21504
	ds_read_b128 v[218:221], v168 offset:22528
	ds_read_b128 v[222:225], v168 offset:23552
	global_load_lds_dwordx4 v[226:227], off
	s_add_i32 m0, s0, 0x2000
	s_add_u32 s0, s34, 0x40000
	v_lshl_add_u64 v[228:229], s[34:35], 0, v[136:137]
	s_addc_u32 s1, s35, 0
	s_add_i32 s77, s59, s39
	global_load_lds_dwordx4 v[228:229], off
	v_lshl_add_u64 v[230:231], s[0:1], 0, v[132:133]
	s_mov_b32 m0, s77
	v_lshl_add_u64 v[232:233], s[36:37], 0, v[134:135]
	global_load_lds_dwordx4 v[230:231], off
	v_lshl_add_u64 v[230:231], s[0:1], 0, v[136:137]
	s_add_i32 m0, s77, 0x2000
	s_nop 0
	global_load_lds_dwordx4 v[230:231], off
	v_lshl_add_u64 v[230:231], s[36:37], 0, v[130:131]
	s_mov_b32 m0, s40
	s_nop 0
	global_load_lds_dwordx4 v[230:231], off
	s_mov_b32 m0, s41
	s_nop 0
	global_load_lds_dwordx4 v[232:233], off
	s_waitcnt vmcnt(8)
	s_waitcnt lgkmcnt(0)
	s_barrier
; #define PG8_STAGE(bufoff, gbase, voff) do { _Pragma("unroll") for (int _i = 0; _i < 2; ++_i) \
;         __builtin_amdgcn_global_load_lds((const unsigned*)((const char*)(gbase) + (voff)[_i]), (PG8_LAS unsigned*)(lds + (bufoff) + ldsw + _i * 8192), 16, 0, 0); } while (0)
; #define PG8_LDA(dst, b, h) do { _Pragma("unroll") for (int m = 0; m < 4; ++m) _Pragma("unroll") for (int k = 0; k < 2; ++k) dst[m][k] = *(const PG8_LAS bf16x8*)(lds + PG8_SA(b, h) + aoff + m * 2048 + k * 1024); } while (0)
; #define PG8_LDB(dst, b, h) do { _Pragma("unroll") for (int n = 0; n < 2; ++n) _Pragma("unroll") for (int k = 0; k < 2; ++k) dst[n][k] = *(const PG8_LAS bf16x8*)(lds + PG8_SB(b, h) + boff + n * 2048 + k * 1024); } while (0)
; #define PG8_MMA(ai, bj, At, Bt) do { __builtin_amdgcn_s_setprio(1); _Pragma("unroll") for (int m = 0; m < 4; ++m) _Pragma("unroll") for (int n = 0; n < 2; ++n) _Pragma("unroll") for (int k = 0; k < 2; ++k) \
;         acc[ai][bj][m][n] = __builtin_amdgcn_mfma_f32_16x16x32_bf16(Bt[n][k], At[m][k], acc[ai][bj][m][n], 0, 0, 0); __builtin_amdgcn_s_setprio(0); } while (0)
; #define PG8_WAIT_V(n) asm volatile("s_waitcnt vmcnt(" #n ")" ::: "memory")
; #define PG8_WAIT_L(n) asm volatile("s_waitcnt lgkmcnt(" #n ")" ::: "memory")
; #define PG8_BAR __builtin_amdgcn_s_barrier()
; #define PG8_SCHED __builtin_amdgcn_sched_barrier(0)
; template <class Epi, class Sched, bool ALIGN_EPI = false, bool SP2 = false>
; __device__ __forceinline__ void gemm_phase(PG8_LAS unsigned char* lds, const Gemm g, const Sched& S, const Epi& E) {
;     ...
;             PG8_WAIT_V(8); PG8_WAIT_L(0); PG8_BAR; PG8_MMA(1, 0, At, B0); PG8_MMA(1, 1, At, B1); PG8_BAR; PG8_SCHED;
;             PG8_LDB(B0, 1, 0); PG8_LDB(B1, 1, 1); PG8_SCHED; PG8_LDA(At, 1, 0); PG8_STAGE(PG8_SA(0, 1), a2 + hstep, voffA);
;             PG8_WAIT_V(8); PG8_WAIT_L(0); PG8_BAR; PG8_MMA(0, 0, At, B0); PG8_MMA(0, 1, At, B1); PG8_BAR; PG8_SCHED;
	s_setprio 1
	v_mfma_f32_16x16x32_bf16 v[62:65], v[144:147], v[192:195], v[62:65]
	v_mfma_f32_16x16x32_bf16 v[58:61], v[152:155], v[192:195], v[58:61]
	v_mfma_f32_16x16x32_bf16 v[46:49], v[144:147], v[200:203], v[46:49]
	v_mfma_f32_16x16x32_bf16 v[42:45], v[152:155], v[200:203], v[42:45]
	v_mfma_f32_16x16x32_bf16 v[30:33], v[144:147], v[210:213], v[30:33]
	v_mfma_f32_16x16x32_bf16 v[26:29], v[152:155], v[210:213], v[26:29]
	v_mfma_f32_16x16x32_bf16 v[14:17], v[144:147], v[218:221], v[14:17]
	v_mfma_f32_16x16x32_bf16 v[10:13], v[152:155], v[218:221], v[10:13]
	v_mfma_f32_16x16x32_bf16 v[62:65], v[148:151], v[196:199], v[62:65]
	v_mfma_f32_16x16x32_bf16 v[58:61], v[172:175], v[196:199], v[58:61]
	v_mfma_f32_16x16x32_bf16 v[46:49], v[148:151], v[204:207], v[46:49]
	v_mfma_f32_16x16x32_bf16 v[42:45], v[172:175], v[204:207], v[42:45]
	v_mfma_f32_16x16x32_bf16 v[30:33], v[148:151], v[214:217], v[30:33]
	v_mfma_f32_16x16x32_bf16 v[26:29], v[172:175], v[214:217], v[26:29]
	v_mfma_f32_16x16x32_bf16 v[14:17], v[148:151], v[222:225], v[14:17]
	v_mfma_f32_16x16x32_bf16 v[10:13], v[172:175], v[222:225], v[10:13]
	v_mfma_f32_16x16x32_bf16 v[54:57], v[176:179], v[192:195], v[54:57]
	v_mfma_f32_16x16x32_bf16 v[50:53], v[184:187], v[192:195], v[50:53]
	v_mfma_f32_16x16x32_bf16 v[38:41], v[176:179], v[200:203], v[38:41]
	v_mfma_f32_16x16x32_bf16 v[34:37], v[184:187], v[200:203], v[34:37]
	v_mfma_f32_16x16x32_bf16 v[22:25], v[176:179], v[210:213], v[22:25]
	v_mfma_f32_16x16x32_bf16 v[18:21], v[184:187], v[210:213], v[18:21]
	v_mfma_f32_16x16x32_bf16 v[6:9], v[176:179], v[218:221], v[6:9]
	v_mfma_f32_16x16x32_bf16 v[2:5], v[184:187], v[218:221], v[2:5]
	v_mfma_f32_16x16x32_bf16 v[54:57], v[180:183], v[196:199], v[54:57]
	v_mfma_f32_16x16x32_bf16 v[50:53], v[188:191], v[196:199], v[50:53]
	v_mfma_f32_16x16x32_bf16 v[38:41], v[180:183], v[204:207], v[38:41]
	v_mfma_f32_16x16x32_bf16 v[34:37], v[188:191], v[204:207], v[34:37]
	v_mfma_f32_16x16x32_bf16 v[22:25], v[180:183], v[214:217], v[22:25]
	v_mfma_f32_16x16x32_bf16 v[18:21], v[188:191], v[214:217], v[18:21]
	v_mfma_f32_16x16x32_bf16 v[6:9], v[180:183], v[222:225], v[6:9]
	v_mfma_f32_16x16x32_bf16 v[2:5], v[188:191], v[222:225], v[2:5]
	s_setprio 0
	s_barrier
	ds_read_b128 v[144:147], v170
	ds_read_b128 v[148:151], v170 offset:1024
	ds_read_b128 v[152:155], v170 offset:2048
	ds_read_b128 v[172:175], v170 offset:3072
	ds_read_b128 v[176:179], v171
	ds_read_b128 v[180:183], v171 offset:1024
	ds_read_b128 v[184:187], v171 offset:2048
	ds_read_b128 v[188:191], v171 offset:3072
	s_add_u32 s0, s36, 0x40000
	s_addc_u32 s1, s37, 0
	s_mov_b32 m0, s43
	v_lshl_add_u64 v[234:235], s[0:1], 0, v[130:131]
	ds_read_b128 v[192:195], v168 offset:32768
	ds_read_b128 v[196:199], v168 offset:33792
	ds_read_b128 v[200:203], v168 offset:34816
	ds_read_b128 v[204:207], v168 offset:35840
	ds_read_b128 v[210:213], v168 offset:36864
	ds_read_b128 v[214:217], v168 offset:37888
	ds_read_b128 v[218:221], v168 offset:38912
	ds_read_b128 v[222:225], v168 offset:39936
	global_load_lds_dwordx4 v[234:235], off
	v_lshl_add_u64 v[234:235], s[0:1], 0, v[134:135]
	s_mov_b32 m0, s52
	s_nop 0
	global_load_lds_dwordx4 v[234:235], off
	s_waitcnt vmcnt(8)
	s_waitcnt lgkmcnt(0)
	s_barrier
	s_setprio 1
	v_mfma_f32_16x16x32_bf16 v[126:129], v[144:147], v[192:195], v[126:129]
	v_mfma_f32_16x16x32_bf16 v[122:125], v[152:155], v[192:195], v[122:125]
	v_mfma_f32_16x16x32_bf16 v[110:113], v[144:147], v[200:203], v[110:113]
	v_mfma_f32_16x16x32_bf16 v[106:109], v[152:155], v[200:203], v[106:109]
	v_mfma_f32_16x16x32_bf16 v[94:97], v[144:147], v[210:213], v[94:97]
	v_mfma_f32_16x16x32_bf16 v[90:93], v[152:155], v[210:213], v[90:93]
	v_mfma_f32_16x16x32_bf16 v[78:81], v[144:147], v[218:221], v[78:81]
	v_mfma_f32_16x16x32_bf16 v[74:77], v[152:155], v[218:221], v[74:77]
	v_mfma_f32_16x16x32_bf16 v[126:129], v[148:151], v[196:199], v[126:129]
	v_mfma_f32_16x16x32_bf16 v[122:125], v[172:175], v[196:199], v[122:125]
	v_mfma_f32_16x16x32_bf16 v[110:113], v[148:151], v[204:207], v[110:113]
	v_mfma_f32_16x16x32_bf16 v[106:109], v[172:175], v[204:207], v[106:109]
	v_mfma_f32_16x16x32_bf16 v[94:97], v[148:151], v[214:217], v[94:97]
	v_mfma_f32_16x16x32_bf16 v[90:93], v[172:175], v[214:217], v[90:93]
	v_mfma_f32_16x16x32_bf16 v[78:81], v[148:151], v[222:225], v[78:81]
	v_mfma_f32_16x16x32_bf16 v[74:77], v[172:175], v[222:225], v[74:77]
	v_mfma_f32_16x16x32_bf16 v[118:121], v[176:179], v[192:195], v[118:121]
	v_mfma_f32_16x16x32_bf16 v[114:117], v[184:187], v[192:195], v[114:117]
	v_mfma_f32_16x16x32_bf16 v[102:105], v[176:179], v[200:203], v[102:105]
	v_mfma_f32_16x16x32_bf16 v[98:101], v[184:187], v[200:203], v[98:101]
	v_mfma_f32_16x16x32_bf16 v[86:89], v[176:179], v[210:213], v[86:89]
	v_mfma_f32_16x16x32_bf16 v[82:85], v[184:187], v[210:213], v[82:85]
	v_mfma_f32_16x16x32_bf16 v[70:73], v[176:179], v[218:221], v[70:73]
	v_mfma_f32_16x16x32_bf16 v[66:69], v[184:187], v[218:221], v[66:69]
	v_mfma_f32_16x16x32_bf16 v[118:121], v[180:183], v[196:199], v[118:121]
	v_mfma_f32_16x16x32_bf16 v[114:117], v[188:191], v[196:199], v[114:117]
	v_mfma_f32_16x16x32_bf16 v[102:105], v[180:183], v[204:207], v[102:105]
	v_mfma_f32_16x16x32_bf16 v[98:101], v[188:191], v[204:207], v[98:101]
	v_mfma_f32_16x16x32_bf16 v[86:89], v[180:183], v[214:217], v[86:89]
	v_mfma_f32_16x16x32_bf16 v[82:85], v[188:191], v[214:217], v[82:85]
	v_mfma_f32_16x16x32_bf16 v[70:73], v[180:183], v[222:225], v[70:73]
	v_mfma_f32_16x16x32_bf16 v[66:69], v[188:191], v[222:225], v[66:69]
	s_setprio 0
	s_barrier
; #define PG8_STAGE(bufoff, gbase, voff) do { _Pragma("unroll") for (int _i = 0; _i < 2; ++_i) \
;         __builtin_amdgcn_global_load_lds((const unsigned*)((const char*)(gbase) + (voff)[_i]), (PG8_LAS unsigned*)(lds + (bufoff) + ldsw + _i * 8192), 16, 0, 0); } while (0)
; #define PG8_LDA(dst, b, h) do { _Pragma("unroll") for (int m = 0; m < 4; ++m) _Pragma("unroll") for (int k = 0; k < 2; ++k) dst[m][k] = *(const PG8_LAS bf16x8*)(lds + PG8_SA(b, h) + aoff + m * 2048 + k * 1024); } while (0)
; #define PG8_MMA(ai, bj, At, Bt) do { __builtin_amdgcn_s_setprio(1); _Pragma("unroll") for (int m = 0; m < 4; ++m) _Pragma("unroll") for (int n = 0; n < 2; ++n) _Pragma("unroll") for (int k = 0; k < 2; ++k) \
;         acc[ai][bj][m][n] = __builtin_amdgcn_mfma_f32_16x16x32_bf16(Bt[n][k], At[m][k], acc[ai][bj][m][n], 0, 0, 0); __builtin_amdgcn_s_setprio(0); } while (0)
; #define PG8_WAIT_V(n) asm volatile("s_waitcnt vmcnt(" #n ")" ::: "memory")
; #define PG8_WAIT_L(n) asm volatile("s_waitcnt lgkmcnt(" #n ")" ::: "memory")
; #define PG8_BAR __builtin_amdgcn_s_barrier()
; #define PG8_SCHED __builtin_amdgcn_sched_barrier(0)
; template <class Epi, class Sched, bool ALIGN_EPI = false, bool SP2 = false>
; __device__ __forceinline__ void gemm_phase(PG8_LAS unsigned char* lds, const Gemm g, const Sched& S, const Epi& E) {
;     ...
;             PG8_LDA(At, 1, 1); PG8_STAGE(PG8_SB(1, 0), b3, voffB); PG8_STAGE(PG8_SB(1, 1), b3 + hstep, voffB); PG8_STAGE(PG8_SA(1, 0), a3, voffA);
;             PG8_WAIT_V(8); PG8_WAIT_L(0); PG8_BAR; PG8_MMA(1, 0, At, B0); PG8_MMA(1, 1, At, B1); PG8_BAR; PG8_SCHED;
	s_add_i32 s0, s69, s39
	v_lshl_add_u64 v[226:227], v[226:227], 0, s[12:13]
	s_mov_b32 m0, s0
	ds_read_b128 v[192:195], v168 offset:49152
	ds_read_b128 v[196:199], v168 offset:50176
	ds_read_b128 v[200:203], v168 offset:51200
	ds_read_b128 v[204:207], v168 offset:52224
	ds_read_b128 v[210:213], v168 offset:53248
	ds_read_b128 v[214:217], v168 offset:54272
	ds_read_b128 v[218:221], v168 offset:55296
	ds_read_b128 v[222:225], v168 offset:56320
	global_load_lds_dwordx4 v[226:227], off
	s_add_i32 m0, s0, 0x2000
	s_add_u32 s0, s34, 0x40080
	v_lshl_add_u64 v[226:227], v[228:229], 0, s[12:13]
	s_addc_u32 s1, s35, 0
	s_add_i32 s34, s82, s39
	global_load_lds_dwordx4 v[226:227], off
	v_lshl_add_u64 v[226:227], s[0:1], 0, v[132:133]
	s_mov_b32 m0, s34
	s_nop 0
	global_load_lds_dwordx4 v[226:227], off
	v_lshl_add_u64 v[226:227], s[0:1], 0, v[136:137]
	s_add_i32 m0, s34, 0x2000
	s_nop 0
	global_load_lds_dwordx4 v[226:227], off
	v_lshl_add_u64 v[226:227], v[230:231], 0, s[12:13]
	s_mov_b32 m0, s54
	s_nop 0
	global_load_lds_dwordx4 v[226:227], off
	v_lshl_add_u64 v[226:227], v[232:233], 0, s[12:13]
	s_mov_b32 m0, s55
	s_nop 0
	global_load_lds_dwordx4 v[226:227], off
	s_waitcnt vmcnt(8)
	s_waitcnt lgkmcnt(0)
	s_barrier
	s_setprio 1
	v_mfma_f32_16x16x32_bf16 v[62:65], v[144:147], v[192:195], v[62:65]
	v_mfma_f32_16x16x32_bf16 v[58:61], v[152:155], v[192:195], v[58:61]
	v_mfma_f32_16x16x32_bf16 v[46:49], v[144:147], v[200:203], v[46:49]
	v_mfma_f32_16x16x32_bf16 v[42:45], v[152:155], v[200:203], v[42:45]
	v_mfma_f32_16x16x32_bf16 v[30:33], v[144:147], v[210:213], v[30:33]
	v_mfma_f32_16x16x32_bf16 v[26:29], v[152:155], v[210:213], v[26:29]
	v_mfma_f32_16x16x32_bf16 v[14:17], v[144:147], v[218:221], v[14:17]
	v_mfma_f32_16x16x32_bf16 v[10:13], v[152:155], v[218:221], v[10:13]
	v_mfma_f32_16x16x32_bf16 v[62:65], v[148:151], v[196:199], v[62:65]
	v_mfma_f32_16x16x32_bf16 v[58:61], v[172:175], v[196:199], v[58:61]
	v_mfma_f32_16x16x32_bf16 v[46:49], v[148:151], v[204:207], v[46:49]
	v_mfma_f32_16x16x32_bf16 v[42:45], v[172:175], v[204:207], v[42:45]
	v_mfma_f32_16x16x32_bf16 v[30:33], v[148:151], v[214:217], v[30:33]
	v_mfma_f32_16x16x32_bf16 v[26:29], v[172:175], v[214:217], v[26:29]
	v_mfma_f32_16x16x32_bf16 v[14:17], v[148:151], v[222:225], v[14:17]
	v_mfma_f32_16x16x32_bf16 v[10:13], v[172:175], v[222:225], v[10:13]
	v_mfma_f32_16x16x32_bf16 v[54:57], v[176:179], v[192:195], v[54:57]
	v_mfma_f32_16x16x32_bf16 v[50:53], v[184:187], v[192:195], v[50:53]
	v_mfma_f32_16x16x32_bf16 v[38:41], v[176:179], v[200:203], v[38:41]
	v_mfma_f32_16x16x32_bf16 v[34:37], v[184:187], v[200:203], v[34:37]
	v_mfma_f32_16x16x32_bf16 v[22:25], v[176:179], v[210:213], v[22:25]
	v_mfma_f32_16x16x32_bf16 v[18:21], v[184:187], v[210:213], v[18:21]
	v_mfma_f32_16x16x32_bf16 v[6:9], v[176:179], v[218:221], v[6:9]
	v_mfma_f32_16x16x32_bf16 v[2:5], v[184:187], v[218:221], v[2:5]
	v_mfma_f32_16x16x32_bf16 v[54:57], v[180:183], v[196:199], v[54:57]
	v_mfma_f32_16x16x32_bf16 v[50:53], v[188:191], v[196:199], v[50:53]
	v_mfma_f32_16x16x32_bf16 v[38:41], v[180:183], v[204:207], v[38:41]
	v_mfma_f32_16x16x32_bf16 v[34:37], v[188:191], v[204:207], v[34:37]
	v_mfma_f32_16x16x32_bf16 v[22:25], v[180:183], v[214:217], v[22:25]
	v_mfma_f32_16x16x32_bf16 v[18:21], v[188:191], v[214:217], v[18:21]
	v_mfma_f32_16x16x32_bf16 v[6:9], v[180:183], v[222:225], v[6:9]
	v_mfma_f32_16x16x32_bf16 v[2:5], v[188:191], v[222:225], v[2:5]
	s_setprio 0
	s_barrier
	s_add_i32 s76, s76, 2
	s_add_u32 s30, s30, 0x100
	s_addc_u32 s31, s31, 0
	s_add_u32 s72, s72, 0x100
	s_addc_u32 s73, s73, 0
	s_cmp_gt_u32 s76, 13
	s_cbranch_scc0 .LBB0_1230
	s_and_b64 vcc, exec, s[14:15]
	s_cbranch_vccz .LBB0_1233
	s_barrier

; #define PG8_STAGE(bufoff, gbase, voff) do { _Pragma("unroll") for (int _i = 0; _i < 2; ++_i) \
;         __builtin_amdgcn_global_load_lds((const unsigned*)((const char*)(gbase) + (voff)[_i]), (PG8_LAS unsigned*)(lds + (bufoff) + ldsw + _i * 8192), 16, 0, 0); } while (0)
; #define PG8_LDA(dst, b, h) do { _Pragma("unroll") for (int m = 0; m < 4; ++m) _Pragma("unroll") for (int k = 0; k < 2; ++k) dst[m][k] = *(const PG8_LAS bf16x8*)(lds + PG8_SA(b, h) + aoff + m * 2048 + k * 1024); } while (0)
; #define PG8_LDB(dst, b, h) do { _Pragma("unroll") for (int n = 0; n < 2; ++n) _Pragma("unroll") for (int k = 0; k < 2; ++k) dst[n][k] = *(const PG8_LAS bf16x8*)(lds + PG8_SB(b, h) + boff + n * 2048 + k * 1024); } while (0)
; #define PG8_MMA(ai, bj, At, Bt) do { __builtin_amdgcn_s_setprio(1); _Pragma("unroll") for (int m = 0; m < 4; ++m) _Pragma("unroll") for (int n = 0; n < 2; ++n) _Pragma("unroll") for (int k = 0; k < 2; ++k) \
;         acc[ai][bj][m][n] = __builtin_amdgcn_mfma_f32_16x16x32_bf16(Bt[n][k], At[m][k], acc[ai][bj][m][n], 0, 0, 0); __builtin_amdgcn_s_setprio(0); } while (0)
; #define PG8_WAIT_V(n) asm volatile("s_waitcnt vmcnt(" #n ")" ::: "memory")
; #define PG8_WAIT_L(n) asm volatile("s_waitcnt lgkmcnt(" #n ")" ::: "memory")
; #define PG8_BAR __builtin_amdgcn_s_barrier()
; #define PG8_SCHED __builtin_amdgcn_sched_barrier(0)
; template <class Epi, class Sched, bool ALIGN_EPI = false, bool SP2 = false>
; __device__ __forceinline__ void gemm_phase(PG8_LAS unsigned char* lds, const Gemm g, const Sched& S, const Epi& E) {
;     ...
;             PG8_LDB(B0, 0, 0); PG8_LDB(B1, 0, 1); PG8_SCHED; PG8_LDA(At, 0, 0); PG8_STAGE(PG8_SA(1, 1), a1 + hstep, voffA);
;             PG8_WAIT_V(8); PG8_WAIT_L(0); PG8_BAR; PG8_MMA(0, 0, At, B0); PG8_MMA(0, 1, At, B1); PG8_BAR; PG8_SCHED;
;             PG8_LDA(At, 0, 1); PG8_STAGE(PG8_SB(0, 0), b2, voffB); PG8_STAGE(PG8_SB(0, 1), b2 + hstep, voffB); PG8_STAGE(PG8_SA(0, 0), a2, voffA);
;             PG8_WAIT_V(8); PG8_WAIT_L(0); PG8_BAR; PG8_MMA(1, 0, At, B0); PG8_MMA(1, 1, At, B1); PG8_BAR; PG8_SCHED;
.LBB0_1267:
	ds_read_b128 v[144:147], v1
	ds_read_b128 v[156:159], v1 offset:1024
	ds_read_b128 v[160:163], v1 offset:2048
	ds_read_b128 v[164:167], v1 offset:3072
	ds_read_b128 v[168:171], v150
	ds_read_b128 v[172:175], v150 offset:1024
	ds_read_b128 v[176:179], v150 offset:2048
	ds_read_b128 v[180:183], v150 offset:3072
	s_add_u32 s0, s28, 0xfffc0080
	s_addc_u32 s1, s29, -1
	s_cmp_eq_u32 s73, 12
	s_cselect_b32 s35, s19, s1
	s_cselect_b32 s34, s27, s0
	s_cselect_b32 s31, s17, s72
	s_cselect_b32 s30, s59, s69
	v_lshl_add_u64 v[218:219], s[28:29], 0, v[138:139]
	s_add_i32 m0, s37, 0xc000
	ds_read_b128 v[184:187], v151
	ds_read_b128 v[188:191], v151 offset:1024
	ds_read_b128 v[192:195], v151 offset:2048
	ds_read_b128 v[196:199], v151 offset:3072
	ds_read_b128 v[200:203], v151 offset:4096
	ds_read_b128 v[204:207], v151 offset:5120
	ds_read_b128 v[210:213], v151 offset:6144
	ds_read_b128 v[214:217], v151 offset:7168
	global_load_lds_dwordx4 v[218:219], off
	v_lshl_add_u64 v[218:219], s[28:29], 0, v[140:141]
	s_add_i32 m0, s37, 0xe000
	s_nop 0
	global_load_lds_dwordx4 v[218:219], off
	s_waitcnt vmcnt(8)
	s_waitcnt lgkmcnt(0)
	s_barrier
	s_setprio 1
	v_mfma_f32_16x16x32_bf16 v[126:129], v[144:147], v[184:187], v[126:129]
	v_mfma_f32_16x16x32_bf16 v[122:125], v[160:163], v[184:187], v[122:125]
	v_mfma_f32_16x16x32_bf16 v[110:113], v[144:147], v[192:195], v[110:113]
	v_mfma_f32_16x16x32_bf16 v[106:109], v[160:163], v[192:195], v[106:109]
	v_mfma_f32_16x16x32_bf16 v[94:97], v[144:147], v[200:203], v[94:97]
	v_mfma_f32_16x16x32_bf16 v[90:93], v[160:163], v[200:203], v[90:93]
	v_mfma_f32_16x16x32_bf16 v[78:81], v[144:147], v[210:213], v[78:81]
	v_mfma_f32_16x16x32_bf16 v[74:77], v[160:163], v[210:213], v[74:77]
	v_mfma_f32_16x16x32_bf16 v[126:129], v[156:159], v[188:191], v[126:129]
	v_mfma_f32_16x16x32_bf16 v[122:125], v[164:167], v[188:191], v[122:125]
	v_mfma_f32_16x16x32_bf16 v[110:113], v[156:159], v[196:199], v[110:113]
	v_mfma_f32_16x16x32_bf16 v[106:109], v[164:167], v[196:199], v[106:109]
	v_mfma_f32_16x16x32_bf16 v[94:97], v[156:159], v[204:207], v[94:97]
	v_mfma_f32_16x16x32_bf16 v[90:93], v[164:167], v[204:207], v[90:93]
	v_mfma_f32_16x16x32_bf16 v[78:81], v[156:159], v[214:217], v[78:81]
	v_mfma_f32_16x16x32_bf16 v[74:77], v[164:167], v[214:217], v[74:77]
	v_mfma_f32_16x16x32_bf16 v[118:121], v[168:171], v[184:187], v[118:121]
	v_mfma_f32_16x16x32_bf16 v[114:117], v[176:179], v[184:187], v[114:117]
	v_mfma_f32_16x16x32_bf16 v[102:105], v[168:171], v[192:195], v[102:105]
	v_mfma_f32_16x16x32_bf16 v[98:101], v[176:179], v[192:195], v[98:101]
	v_mfma_f32_16x16x32_bf16 v[86:89], v[168:171], v[200:203], v[86:89]
	v_mfma_f32_16x16x32_bf16 v[82:85], v[176:179], v[200:203], v[82:85]
	v_mfma_f32_16x16x32_bf16 v[70:73], v[168:171], v[210:213], v[70:73]
	v_mfma_f32_16x16x32_bf16 v[66:69], v[176:179], v[210:213], v[66:69]
	v_mfma_f32_16x16x32_bf16 v[118:121], v[172:175], v[188:191], v[118:121]
	v_mfma_f32_16x16x32_bf16 v[114:117], v[180:183], v[188:191], v[114:117]
	v_mfma_f32_16x16x32_bf16 v[102:105], v[172:175], v[196:199], v[102:105]
	v_mfma_f32_16x16x32_bf16 v[98:101], v[180:183], v[196:199], v[98:101]
	v_mfma_f32_16x16x32_bf16 v[86:89], v[172:175], v[204:207], v[86:89]
	v_mfma_f32_16x16x32_bf16 v[82:85], v[180:183], v[204:207], v[82:85]
	v_mfma_f32_16x16x32_bf16 v[70:73], v[172:175], v[214:217], v[70:73]
	v_mfma_f32_16x16x32_bf16 v[66:69], v[180:183], v[214:217], v[66:69]
	s_setprio 0
	s_barrier
	s_add_i32 s0, s54, s36
	v_lshl_add_u64 v[218:219], s[30:31], 0, v[132:133]
	s_mov_b32 m0, s0
	ds_read_b128 v[184:187], v151 offset:16384
	ds_read_b128 v[188:191], v151 offset:17408
	ds_read_b128 v[192:195], v151 offset:18432
	ds_read_b128 v[196:199], v151 offset:19456
	ds_read_b128 v[200:203], v151 offset:20480
	ds_read_b128 v[204:207], v151 offset:21504
	ds_read_b128 v[210:213], v151 offset:22528
	ds_read_b128 v[214:217], v151 offset:23552
	global_load_lds_dwordx4 v[218:219], off
	s_add_i32 m0, s0, 0x2000
	s_add_u32 s0, s30, 0x40000
	v_lshl_add_u64 v[220:221], s[30:31], 0, v[136:137]
	s_addc_u32 s1, s31, 0
	s_add_i32 s76, s55, s36
	global_load_lds_dwordx4 v[220:221], off
	v_lshl_add_u64 v[222:223], s[0:1], 0, v[132:133]
	s_mov_b32 m0, s76
	v_lshl_add_u64 v[224:225], s[34:35], 0, v[134:135]
	global_load_lds_dwordx4 v[222:223], off
	v_lshl_add_u64 v[222:223], s[0:1], 0, v[136:137]
	s_add_i32 m0, s76, 0x2000
	s_nop 0
	global_load_lds_dwordx4 v[222:223], off
	v_lshl_add_u64 v[222:223], s[34:35], 0, v[130:131]
	s_mov_b32 m0, s37
	s_nop 0
	global_load_lds_dwordx4 v[222:223], off
	s_mov_b32 m0, s39
	s_nop 0
	global_load_lds_dwordx4 v[224:225], off
	s_waitcnt vmcnt(8)
	s_waitcnt lgkmcnt(0)
	s_barrier
; #define PG8_STAGE(bufoff, gbase, voff) do { _Pragma("unroll") for (int _i = 0; _i < 2; ++_i) \
;         __builtin_amdgcn_global_load_lds((const unsigned*)((const char*)(gbase) + (voff)[_i]), (PG8_LAS unsigned*)(lds + (bufoff) + ldsw + _i * 8192), 16, 0, 0); } while (0)
; #define PG8_LDA(dst, b, h) do { _Pragma("unroll") for (int m = 0; m < 4; ++m) _Pragma("unroll") for (int k = 0; k < 2; ++k) dst[m][k] = *(const PG8_LAS bf16x8*)(lds + PG8_SA(b, h) + aoff + m * 2048 + k * 1024); } while (0)
; #define PG8_LDB(dst, b, h) do { _Pragma("unroll") for (int n = 0; n < 2; ++n) _Pragma("unroll") for (int k = 0; k < 2; ++k) dst[n][k] = *(const PG8_LAS bf16x8*)(lds + PG8_SB(b, h) + boff + n * 2048 + k * 1024); } while (0)
; #define PG8_MMA(ai, bj, At, Bt) do { __builtin_amdgcn_s_setprio(1); _Pragma("unroll") for (int m = 0; m < 4; ++m) _Pragma("unroll") for (int n = 0; n < 2; ++n) _Pragma("unroll") for (int k = 0; k < 2; ++k) \
;         acc[ai][bj][m][n] = __builtin_amdgcn_mfma_f32_16x16x32_bf16(Bt[n][k], At[m][k], acc[ai][bj][m][n], 0, 0, 0); __builtin_amdgcn_s_setprio(0); } while (0)
; #define PG8_WAIT_V(n) asm volatile("s_waitcnt vmcnt(" #n ")" ::: "memory")
; #define PG8_WAIT_L(n) asm volatile("s_waitcnt lgkmcnt(" #n ")" ::: "memory")
; #define PG8_BAR __builtin_amdgcn_s_barrier()
; #define PG8_SCHED __builtin_amdgcn_sched_barrier(0)
; template <class Epi, class Sched, bool ALIGN_EPI = false, bool SP2 = false>
; __device__ __forceinline__ void gemm_phase(PG8_LAS unsigned char* lds, const Gemm g, const Sched& S, const Epi& E) {
;     ...
;             PG8_WAIT_V(8); PG8_WAIT_L(0); PG8_BAR; PG8_MMA(1, 0, At, B0); PG8_MMA(1, 1, At, B1); PG8_BAR; PG8_SCHED;
;             PG8_LDB(B0, 1, 0); PG8_LDB(B1, 1, 1); PG8_SCHED; PG8_LDA(At, 1, 0); PG8_STAGE(PG8_SA(0, 1), a2 + hstep, voffA);
;             PG8_WAIT_V(8); PG8_WAIT_L(0); PG8_BAR; PG8_MMA(0, 0, At, B0); PG8_MMA(0, 1, At, B1); PG8_BAR; PG8_SCHED;
	s_setprio 1
	v_mfma_f32_16x16x32_bf16 v[62:65], v[144:147], v[184:187], v[62:65]
	v_mfma_f32_16x16x32_bf16 v[58:61], v[160:163], v[184:187], v[58:61]
	v_mfma_f32_16x16x32_bf16 v[46:49], v[144:147], v[192:195], v[46:49]
	v_mfma_f32_16x16x32_bf16 v[42:45], v[160:163], v[192:195], v[42:45]
	v_mfma_f32_16x16x32_bf16 v[30:33], v[144:147], v[200:203], v[30:33]
	v_mfma_f32_16x16x32_bf16 v[26:29], v[160:163], v[200:203], v[26:29]
	v_mfma_f32_16x16x32_bf16 v[14:17], v[144:147], v[210:213], v[14:17]
	v_mfma_f32_16x16x32_bf16 v[10:13], v[160:163], v[210:213], v[10:13]
	v_mfma_f32_16x16x32_bf16 v[62:65], v[156:159], v[188:191], v[62:65]
	v_mfma_f32_16x16x32_bf16 v[58:61], v[164:167], v[188:191], v[58:61]
	v_mfma_f32_16x16x32_bf16 v[46:49], v[156:159], v[196:199], v[46:49]
	v_mfma_f32_16x16x32_bf16 v[42:45], v[164:167], v[196:199], v[42:45]
	v_mfma_f32_16x16x32_bf16 v[30:33], v[156:159], v[204:207], v[30:33]
	v_mfma_f32_16x16x32_bf16 v[26:29], v[164:167], v[204:207], v[26:29]
	v_mfma_f32_16x16x32_bf16 v[14:17], v[156:159], v[214:217], v[14:17]
	v_mfma_f32_16x16x32_bf16 v[10:13], v[164:167], v[214:217], v[10:13]
	v_mfma_f32_16x16x32_bf16 v[54:57], v[168:171], v[184:187], v[54:57]
	v_mfma_f32_16x16x32_bf16 v[50:53], v[176:179], v[184:187], v[50:53]
	v_mfma_f32_16x16x32_bf16 v[38:41], v[168:171], v[192:195], v[38:41]
	v_mfma_f32_16x16x32_bf16 v[34:37], v[176:179], v[192:195], v[34:37]
	v_mfma_f32_16x16x32_bf16 v[22:25], v[168:171], v[200:203], v[22:25]
	v_mfma_f32_16x16x32_bf16 v[18:21], v[176:179], v[200:203], v[18:21]
	v_mfma_f32_16x16x32_bf16 v[6:9], v[168:171], v[210:213], v[6:9]
	v_mfma_f32_16x16x32_bf16 v[2:5], v[176:179], v[210:213], v[2:5]
	v_mfma_f32_16x16x32_bf16 v[54:57], v[172:175], v[188:191], v[54:57]
	v_mfma_f32_16x16x32_bf16 v[50:53], v[180:183], v[188:191], v[50:53]
	v_mfma_f32_16x16x32_bf16 v[38:41], v[172:175], v[196:199], v[38:41]
	v_mfma_f32_16x16x32_bf16 v[34:37], v[180:183], v[196:199], v[34:37]
	v_mfma_f32_16x16x32_bf16 v[22:25], v[172:175], v[204:207], v[22:25]
	v_mfma_f32_16x16x32_bf16 v[18:21], v[180:183], v[204:207], v[18:21]
	v_mfma_f32_16x16x32_bf16 v[6:9], v[172:175], v[214:217], v[6:9]
	v_mfma_f32_16x16x32_bf16 v[2:5], v[180:183], v[214:217], v[2:5]
	s_setprio 0
	s_barrier
	ds_read_b128 v[144:147], v153
	ds_read_b128 v[156:159], v153 offset:1024
	ds_read_b128 v[160:163], v153 offset:2048
	ds_read_b128 v[164:167], v153 offset:3072
	ds_read_b128 v[168:171], v154
	ds_read_b128 v[172:175], v154 offset:1024
	ds_read_b128 v[176:179], v154 offset:2048
	ds_read_b128 v[180:183], v154 offset:3072
	s_add_u32 s0, s34, 0x40000
	s_addc_u32 s1, s35, 0
	s_mov_b32 m0, s40
	v_lshl_add_u64 v[226:227], s[0:1], 0, v[130:131]
	ds_read_b128 v[184:187], v151 offset:32768
	ds_read_b128 v[188:191], v151 offset:33792
	ds_read_b128 v[192:195], v151 offset:34816
	ds_read_b128 v[196:199], v151 offset:35840
	ds_read_b128 v[200:203], v151 offset:36864
	ds_read_b128 v[204:207], v151 offset:37888
	ds_read_b128 v[210:213], v151 offset:38912
	ds_read_b128 v[214:217], v151 offset:39936
	global_load_lds_dwordx4 v[226:227], off
	v_lshl_add_u64 v[226:227], s[0:1], 0, v[134:135]
	s_mov_b32 m0, s41
	s_nop 0
	global_load_lds_dwordx4 v[226:227], off
	s_waitcnt vmcnt(8)
	s_waitcnt lgkmcnt(0)
	s_barrier
	s_setprio 1
	v_mfma_f32_16x16x32_bf16 v[126:129], v[144:147], v[184:187], v[126:129]
	v_mfma_f32_16x16x32_bf16 v[122:125], v[160:163], v[184:187], v[122:125]
	v_mfma_f32_16x16x32_bf16 v[110:113], v[144:147], v[192:195], v[110:113]
	v_mfma_f32_16x16x32_bf16 v[106:109], v[160:163], v[192:195], v[106:109]
	v_mfma_f32_16x16x32_bf16 v[94:97], v[144:147], v[200:203], v[94:97]
	v_mfma_f32_16x16x32_bf16 v[90:93], v[160:163], v[200:203], v[90:93]
	v_mfma_f32_16x16x32_bf16 v[78:81], v[144:147], v[210:213], v[78:81]
	v_mfma_f32_16x16x32_bf16 v[74:77], v[160:163], v[210:213], v[74:77]
	v_mfma_f32_16x16x32_bf16 v[126:129], v[156:159], v[188:191], v[126:129]
	v_mfma_f32_16x16x32_bf16 v[122:125], v[164:167], v[188:191], v[122:125]
	v_mfma_f32_16x16x32_bf16 v[110:113], v[156:159], v[196:199], v[110:113]
	v_mfma_f32_16x16x32_bf16 v[106:109], v[164:167], v[196:199], v[106:109]
	v_mfma_f32_16x16x32_bf16 v[94:97], v[156:159], v[204:207], v[94:97]
	v_mfma_f32_16x16x32_bf16 v[90:93], v[164:167], v[204:207], v[90:93]
	v_mfma_f32_16x16x32_bf16 v[78:81], v[156:159], v[214:217], v[78:81]
	v_mfma_f32_16x16x32_bf16 v[74:77], v[164:167], v[214:217], v[74:77]
	v_mfma_f32_16x16x32_bf16 v[118:121], v[168:171], v[184:187], v[118:121]
	v_mfma_f32_16x16x32_bf16 v[114:117], v[176:179], v[184:187], v[114:117]
	v_mfma_f32_16x16x32_bf16 v[102:105], v[168:171], v[192:195], v[102:105]
	v_mfma_f32_16x16x32_bf16 v[98:101], v[176:179], v[192:195], v[98:101]
	v_mfma_f32_16x16x32_bf16 v[86:89], v[168:171], v[200:203], v[86:89]
	v_mfma_f32_16x16x32_bf16 v[82:85], v[176:179], v[200:203], v[82:85]
	v_mfma_f32_16x16x32_bf16 v[70:73], v[168:171], v[210:213], v[70:73]
	v_mfma_f32_16x16x32_bf16 v[66:69], v[176:179], v[210:213], v[66:69]
	v_mfma_f32_16x16x32_bf16 v[118:121], v[172:175], v[188:191], v[118:121]
	v_mfma_f32_16x16x32_bf16 v[114:117], v[180:183], v[188:191], v[114:117]
	v_mfma_f32_16x16x32_bf16 v[102:105], v[172:175], v[196:199], v[102:105]
	v_mfma_f32_16x16x32_bf16 v[98:101], v[180:183], v[196:199], v[98:101]
	v_mfma_f32_16x16x32_bf16 v[86:89], v[172:175], v[204:207], v[86:89]
	v_mfma_f32_16x16x32_bf16 v[82:85], v[180:183], v[204:207], v[82:85]
	v_mfma_f32_16x16x32_bf16 v[70:73], v[172:175], v[214:217], v[70:73]
	v_mfma_f32_16x16x32_bf16 v[66:69], v[180:183], v[214:217], v[66:69]
	s_setprio 0
	s_barrier
; #define PG8_STAGE(bufoff, gbase, voff) do { _Pragma("unroll") for (int _i = 0; _i < 2; ++_i) \
;         __builtin_amdgcn_global_load_lds((const unsigned*)((const char*)(gbase) + (voff)[_i]), (PG8_LAS unsigned*)(lds + (bufoff) + ldsw + _i * 8192), 16, 0, 0); } while (0)
; #define PG8_LDA(dst, b, h) do { _Pragma("unroll") for (int m = 0; m < 4; ++m) _Pragma("unroll") for (int k = 0; k < 2; ++k) dst[m][k] = *(const PG8_LAS bf16x8*)(lds + PG8_SA(b, h) + aoff + m * 2048 + k * 1024); } while (0)
; #define PG8_MMA(ai, bj, At, Bt) do { __builtin_amdgcn_s_setprio(1); _Pragma("unroll") for (int m = 0; m < 4; ++m) _Pragma("unroll") for (int n = 0; n < 2; ++n) _Pragma("unroll") for (int k = 0; k < 2; ++k) \
;         acc[ai][bj][m][n] = __builtin_amdgcn_mfma_f32_16x16x32_bf16(Bt[n][k], At[m][k], acc[ai][bj][m][n], 0, 0, 0); __builtin_amdgcn_s_setprio(0); } while (0)
; #define PG8_WAIT_V(n) asm volatile("s_waitcnt vmcnt(" #n ")" ::: "memory")
; #define PG8_WAIT_L(n) asm volatile("s_waitcnt lgkmcnt(" #n ")" ::: "memory")
; #define PG8_BAR __builtin_amdgcn_s_barrier()
; #define PG8_SCHED __builtin_amdgcn_sched_barrier(0)
; template <class Epi, class Sched, bool ALIGN_EPI = false, bool SP2 = false>
; __device__ __forceinline__ void gemm_phase(PG8_LAS unsigned char* lds, const Gemm g, const Sched& S, const Epi& E) {
;     ...
;             PG8_LDA(At, 1, 1); PG8_STAGE(PG8_SB(1, 0), b3, voffB); PG8_STAGE(PG8_SB(1, 1), b3 + hstep, voffB); PG8_STAGE(PG8_SA(1, 0), a3, voffA);
;             PG8_WAIT_V(8); PG8_WAIT_L(0); PG8_BAR; PG8_MMA(1, 0, At, B0); PG8_MMA(1, 1, At, B1); PG8_BAR; PG8_SCHED;
	s_add_i32 s0, s56, s36
	v_lshl_add_u64 v[218:219], v[218:219], 0, s[10:11]
	s_mov_b32 m0, s0
	ds_read_b128 v[184:187], v151 offset:49152
	ds_read_b128 v[188:191], v151 offset:50176
	ds_read_b128 v[192:195], v151 offset:51200
	ds_read_b128 v[196:199], v151 offset:52224
	ds_read_b128 v[200:203], v151 offset:53248
	ds_read_b128 v[204:207], v151 offset:54272
	ds_read_b128 v[210:213], v151 offset:55296
	ds_read_b128 v[214:217], v151 offset:56320
	global_load_lds_dwordx4 v[218:219], off
	s_add_i32 m0, s0, 0x2000
	s_add_u32 s0, s30, 0x40080
	v_lshl_add_u64 v[218:219], v[220:221], 0, s[10:11]
	s_addc_u32 s1, s31, 0
	s_add_i32 s30, s57, s36
	global_load_lds_dwordx4 v[218:219], off
	v_lshl_add_u64 v[218:219], s[0:1], 0, v[132:133]
	s_mov_b32 m0, s30
	s_nop 0
	global_load_lds_dwordx4 v[218:219], off
	v_lshl_add_u64 v[218:219], s[0:1], 0, v[136:137]
	s_add_i32 m0, s30, 0x2000
	s_nop 0
	global_load_lds_dwordx4 v[218:219], off
	v_lshl_add_u64 v[218:219], v[222:223], 0, s[10:11]
	s_mov_b32 m0, s48
	s_nop 0
	global_load_lds_dwordx4 v[218:219], off
	v_lshl_add_u64 v[218:219], v[224:225], 0, s[10:11]
	s_mov_b32 m0, s49
	s_nop 0
	global_load_lds_dwordx4 v[218:219], off
	s_waitcnt vmcnt(8)
	s_waitcnt lgkmcnt(0)
	s_barrier
	s_setprio 1
	v_mfma_f32_16x16x32_bf16 v[62:65], v[144:147], v[184:187], v[62:65]
	v_mfma_f32_16x16x32_bf16 v[58:61], v[160:163], v[184:187], v[58:61]
	v_mfma_f32_16x16x32_bf16 v[46:49], v[144:147], v[192:195], v[46:49]
	v_mfma_f32_16x16x32_bf16 v[42:45], v[160:163], v[192:195], v[42:45]
	v_mfma_f32_16x16x32_bf16 v[30:33], v[144:147], v[200:203], v[30:33]
	v_mfma_f32_16x16x32_bf16 v[26:29], v[160:163], v[200:203], v[26:29]
	v_mfma_f32_16x16x32_bf16 v[14:17], v[144:147], v[210:213], v[14:17]
	v_mfma_f32_16x16x32_bf16 v[10:13], v[160:163], v[210:213], v[10:13]
	v_mfma_f32_16x16x32_bf16 v[62:65], v[156:159], v[188:191], v[62:65]
	v_mfma_f32_16x16x32_bf16 v[58:61], v[164:167], v[188:191], v[58:61]
	v_mfma_f32_16x16x32_bf16 v[46:49], v[156:159], v[196:199], v[46:49]
	v_mfma_f32_16x16x32_bf16 v[42:45], v[164:167], v[196:199], v[42:45]
	v_mfma_f32_16x16x32_bf16 v[30:33], v[156:159], v[204:207], v[30:33]
	v_mfma_f32_16x16x32_bf16 v[26:29], v[164:167], v[204:207], v[26:29]
	v_mfma_f32_16x16x32_bf16 v[14:17], v[156:159], v[214:217], v[14:17]
	v_mfma_f32_16x16x32_bf16 v[10:13], v[164:167], v[214:217], v[10:13]
	v_mfma_f32_16x16x32_bf16 v[54:57], v[168:171], v[184:187], v[54:57]
	v_mfma_f32_16x16x32_bf16 v[50:53], v[176:179], v[184:187], v[50:53]
	v_mfma_f32_16x16x32_bf16 v[38:41], v[168:171], v[192:195], v[38:41]
	v_mfma_f32_16x16x32_bf16 v[34:37], v[176:179], v[192:195], v[34:37]
	v_mfma_f32_16x16x32_bf16 v[22:25], v[168:171], v[200:203], v[22:25]
	v_mfma_f32_16x16x32_bf16 v[18:21], v[176:179], v[200:203], v[18:21]
	v_mfma_f32_16x16x32_bf16 v[6:9], v[168:171], v[210:213], v[6:9]
	v_mfma_f32_16x16x32_bf16 v[2:5], v[176:179], v[210:213], v[2:5]
	v_mfma_f32_16x16x32_bf16 v[54:57], v[172:175], v[188:191], v[54:57]
	v_mfma_f32_16x16x32_bf16 v[50:53], v[180:183], v[188:191], v[50:53]
	v_mfma_f32_16x16x32_bf16 v[38:41], v[172:175], v[196:199], v[38:41]
	v_mfma_f32_16x16x32_bf16 v[34:37], v[180:183], v[196:199], v[34:37]
	v_mfma_f32_16x16x32_bf16 v[22:25], v[172:175], v[204:207], v[22:25]
	v_mfma_f32_16x16x32_bf16 v[18:21], v[180:183], v[204:207], v[18:21]
	v_mfma_f32_16x16x32_bf16 v[6:9], v[172:175], v[214:217], v[6:9]
	v_mfma_f32_16x16x32_bf16 v[2:5], v[180:183], v[214:217], v[2:5]
	s_setprio 0
	s_barrier
	s_add_i32 s73, s73, 2
	s_add_u32 s28, s28, 0x100
	s_addc_u32 s29, s29, 0
	s_add_u32 s69, s69, 0x100
	s_addc_u32 s72, s72, 0
	s_cmp_gt_u32 s73, 13
	s_cbranch_scc0 .LBB0_1267
	s_and_b64 vcc, exec, s[12:13]
	s_cbranch_vccz .LBB0_1270
	s_barrier

; #define PG8_STAGE(bufoff, gbase, voff) do { _Pragma("unroll") for (int _i = 0; _i < 2; ++_i) \
;         __builtin_amdgcn_global_load_lds((const unsigned*)((const char*)(gbase) + (voff)[_i]), (PG8_LAS unsigned*)(lds + (bufoff) + ldsw + _i * 8192), 16, 0, 0); } while (0)
; #define PG8_LDA(dst, b, h) do { _Pragma("unroll") for (int m = 0; m < 4; ++m) _Pragma("unroll") for (int k = 0; k < 2; ++k) dst[m][k] = *(const PG8_LAS bf16x8*)(lds + PG8_SA(b, h) + aoff + m * 2048 + k * 1024); } while (0)
; #define PG8_LDB(dst, b, h) do { _Pragma("unroll") for (int n = 0; n < 2; ++n) _Pragma("unroll") for (int k = 0; k < 2; ++k) dst[n][k] = *(const PG8_LAS bf16x8*)(lds + PG8_SB(b, h) + boff + n * 2048 + k * 1024); } while (0)
; #define PG8_MMA(ai, bj, At, Bt) do { __builtin_amdgcn_s_setprio(1); _Pragma("unroll") for (int m = 0; m < 4; ++m) _Pragma("unroll") for (int n = 0; n < 2; ++n) _Pragma("unroll") for (int k = 0; k < 2; ++k) \
;         acc[ai][bj][m][n] = __builtin_amdgcn_mfma_f32_16x16x32_bf16(Bt[n][k], At[m][k], acc[ai][bj][m][n], 0, 0, 0); __builtin_amdgcn_s_setprio(0); } while (0)
; #define PG8_WAIT_V(n) asm volatile("s_waitcnt vmcnt(" #n ")" ::: "memory")
; #define PG8_WAIT_L(n) asm volatile("s_waitcnt lgkmcnt(" #n ")" ::: "memory")
; #define PG8_BAR __builtin_amdgcn_s_barrier()
; #define PG8_SCHED __builtin_amdgcn_sched_barrier(0)
; template <class Epi, class Sched, bool ALIGN_EPI = false, bool SP2 = false>
; __device__ __forceinline__ void gemm_phase(PG8_LAS unsigned char* lds, const Gemm g, const Sched& S, const Epi& E) {
;     ...
;             PG8_LDB(B0, 0, 0); PG8_LDB(B1, 0, 1); PG8_SCHED; PG8_LDA(At, 0, 0); PG8_STAGE(PG8_SA(1, 1), a1 + hstep, voffA);
;             PG8_WAIT_V(8); PG8_WAIT_L(0); PG8_BAR; PG8_MMA(0, 0, At, B0); PG8_MMA(0, 1, At, B1); PG8_BAR; PG8_SCHED;
;             PG8_LDA(At, 0, 1); PG8_STAGE(PG8_SB(0, 0), b2, voffB); PG8_STAGE(PG8_SB(0, 1), b2 + hstep, voffB); PG8_STAGE(PG8_SA(0, 0), a2, voffA);
;             PG8_WAIT_V(8); PG8_WAIT_L(0); PG8_BAR; PG8_MMA(1, 0, At, B0); PG8_MMA(1, 1, At, B1); PG8_BAR; PG8_SCHED;
.LBB0_1380:
	ds_read_b128 v[146:149], v153
	ds_read_b128 v[160:163], v153 offset:1024
	ds_read_b128 v[164:167], v153 offset:2048
	ds_read_b128 v[168:171], v153 offset:3072
	ds_read_b128 v[172:175], v154
	ds_read_b128 v[176:179], v154 offset:1024
	ds_read_b128 v[180:183], v154 offset:2048
	ds_read_b128 v[184:187], v154 offset:3072
	s_add_u32 s0, s4, 0xfffc0080
	s_addc_u32 s1, s5, -1
	s_cmp_eq_u32 s54, 12
	s_cselect_b32 s29, s15, s1
	s_cselect_b32 s28, s25, s0
	s_cselect_b32 s27, s9, s53
	s_cselect_b32 s26, s49, s52
	v_lshl_add_u64 v[222:223], s[4:5], 0, v[140:141]
	s_add_i32 m0, s34, 0xc000
	ds_read_b128 v[188:191], v155
	ds_read_b128 v[192:195], v155 offset:1024
	ds_read_b128 v[196:199], v155 offset:2048
	ds_read_b128 v[200:203], v155 offset:3072
	ds_read_b128 v[204:207], v155 offset:4096
	ds_read_b128 v[210:213], v155 offset:5120
	ds_read_b128 v[214:217], v155 offset:6144
	ds_read_b128 v[218:221], v155 offset:7168
	global_load_lds_dwordx4 v[222:223], off
	v_lshl_add_u64 v[222:223], s[4:5], 0, v[142:143]
	s_add_i32 m0, s34, 0xe000
	s_nop 0
	global_load_lds_dwordx4 v[222:223], off
	s_waitcnt vmcnt(8)
	s_waitcnt lgkmcnt(0)
	s_barrier
	s_setprio 1
	v_mfma_f32_16x16x32_bf16 v[126:129], v[146:149], v[188:191], v[126:129]
	v_mfma_f32_16x16x32_bf16 v[122:125], v[164:167], v[188:191], v[122:125]
	v_mfma_f32_16x16x32_bf16 v[110:113], v[146:149], v[196:199], v[110:113]
	v_mfma_f32_16x16x32_bf16 v[106:109], v[164:167], v[196:199], v[106:109]
	v_mfma_f32_16x16x32_bf16 v[94:97], v[146:149], v[204:207], v[94:97]
	v_mfma_f32_16x16x32_bf16 v[90:93], v[164:167], v[204:207], v[90:93]
	v_mfma_f32_16x16x32_bf16 v[78:81], v[146:149], v[214:217], v[78:81]
	v_mfma_f32_16x16x32_bf16 v[74:77], v[164:167], v[214:217], v[74:77]
	v_mfma_f32_16x16x32_bf16 v[126:129], v[160:163], v[192:195], v[126:129]
	v_mfma_f32_16x16x32_bf16 v[122:125], v[168:171], v[192:195], v[122:125]
	v_mfma_f32_16x16x32_bf16 v[110:113], v[160:163], v[200:203], v[110:113]
	v_mfma_f32_16x16x32_bf16 v[106:109], v[168:171], v[200:203], v[106:109]
	v_mfma_f32_16x16x32_bf16 v[94:97], v[160:163], v[210:213], v[94:97]
	v_mfma_f32_16x16x32_bf16 v[90:93], v[168:171], v[210:213], v[90:93]
	v_mfma_f32_16x16x32_bf16 v[78:81], v[160:163], v[218:221], v[78:81]
	v_mfma_f32_16x16x32_bf16 v[74:77], v[168:171], v[218:221], v[74:77]
	v_mfma_f32_16x16x32_bf16 v[118:121], v[172:175], v[188:191], v[118:121]
	v_mfma_f32_16x16x32_bf16 v[114:117], v[180:183], v[188:191], v[114:117]
	v_mfma_f32_16x16x32_bf16 v[102:105], v[172:175], v[196:199], v[102:105]
	v_mfma_f32_16x16x32_bf16 v[98:101], v[180:183], v[196:199], v[98:101]
	v_mfma_f32_16x16x32_bf16 v[86:89], v[172:175], v[204:207], v[86:89]
	v_mfma_f32_16x16x32_bf16 v[82:85], v[180:183], v[204:207], v[82:85]
	v_mfma_f32_16x16x32_bf16 v[70:73], v[172:175], v[214:217], v[70:73]
	v_mfma_f32_16x16x32_bf16 v[66:69], v[180:183], v[214:217], v[66:69]
	v_mfma_f32_16x16x32_bf16 v[118:121], v[176:179], v[192:195], v[118:121]
	v_mfma_f32_16x16x32_bf16 v[114:117], v[184:187], v[192:195], v[114:117]
	v_mfma_f32_16x16x32_bf16 v[102:105], v[176:179], v[200:203], v[102:105]
	v_mfma_f32_16x16x32_bf16 v[98:101], v[184:187], v[200:203], v[98:101]
	v_mfma_f32_16x16x32_bf16 v[86:89], v[176:179], v[210:213], v[86:89]
	v_mfma_f32_16x16x32_bf16 v[82:85], v[184:187], v[210:213], v[82:85]
	v_mfma_f32_16x16x32_bf16 v[70:73], v[176:179], v[218:221], v[70:73]
	v_mfma_f32_16x16x32_bf16 v[66:69], v[184:187], v[218:221], v[66:69]
	s_setprio 0
	s_barrier
	s_add_i32 s0, s41, s31
	v_lshl_add_u64 v[222:223], s[26:27], 0, v[132:133]
	s_mov_b32 m0, s0
	ds_read_b128 v[188:191], v155 offset:16384
	ds_read_b128 v[192:195], v155 offset:17408
	ds_read_b128 v[196:199], v155 offset:18432
	ds_read_b128 v[200:203], v155 offset:19456
	ds_read_b128 v[204:207], v155 offset:20480
	ds_read_b128 v[210:213], v155 offset:21504
	ds_read_b128 v[214:217], v155 offset:22528
	ds_read_b128 v[218:221], v155 offset:23552
	global_load_lds_dwordx4 v[222:223], off
	s_add_i32 m0, s0, 0x2000
	s_add_u32 s0, s26, 0x40000
	v_lshl_add_u64 v[224:225], s[26:27], 0, v[136:137]
	s_addc_u32 s1, s27, 0
	s_add_i32 s55, s44, s31
	global_load_lds_dwordx4 v[224:225], off
	v_lshl_add_u64 v[226:227], s[0:1], 0, v[132:133]
	s_mov_b32 m0, s55
	v_lshl_add_u64 v[228:229], s[28:29], 0, v[134:135]
	global_load_lds_dwordx4 v[226:227], off
	v_lshl_add_u64 v[226:227], s[0:1], 0, v[136:137]
	s_add_i32 m0, s55, 0x2000
	s_nop 0
	global_load_lds_dwordx4 v[226:227], off
	v_lshl_add_u64 v[226:227], s[28:29], 0, v[130:131]
	s_mov_b32 m0, s34
	s_nop 0
	global_load_lds_dwordx4 v[226:227], off
	s_mov_b32 m0, s35
	s_nop 0
	global_load_lds_dwordx4 v[228:229], off
	s_waitcnt vmcnt(8)
	s_waitcnt lgkmcnt(0)
	s_barrier
; #define PG8_STAGE(bufoff, gbase, voff) do { _Pragma("unroll") for (int _i = 0; _i < 2; ++_i) \
;         __builtin_amdgcn_global_load_lds((const unsigned*)((const char*)(gbase) + (voff)[_i]), (PG8_LAS unsigned*)(lds + (bufoff) + ldsw + _i * 8192), 16, 0, 0); } while (0)
; #define PG8_LDA(dst, b, h) do { _Pragma("unroll") for (int m = 0; m < 4; ++m) _Pragma("unroll") for (int k = 0; k < 2; ++k) dst[m][k] = *(const PG8_LAS bf16x8*)(lds + PG8_SA(b, h) + aoff + m * 2048 + k * 1024); } while (0)
; #define PG8_LDB(dst, b, h) do { _Pragma("unroll") for (int n = 0; n < 2; ++n) _Pragma("unroll") for (int k = 0; k < 2; ++k) dst[n][k] = *(const PG8_LAS bf16x8*)(lds + PG8_SB(b, h) + boff + n * 2048 + k * 1024); } while (0)
; #define PG8_MMA(ai, bj, At, Bt) do { __builtin_amdgcn_s_setprio(1); _Pragma("unroll") for (int m = 0; m < 4; ++m) _Pragma("unroll") for (int n = 0; n < 2; ++n) _Pragma("unroll") for (int k = 0; k < 2; ++k) \
;         acc[ai][bj][m][n] = __builtin_amdgcn_mfma_f32_16x16x32_bf16(Bt[n][k], At[m][k], acc[ai][bj][m][n], 0, 0, 0); __builtin_amdgcn_s_setprio(0); } while (0)
; #define PG8_WAIT_V(n) asm volatile("s_waitcnt vmcnt(" #n ")" ::: "memory")
; #define PG8_WAIT_L(n) asm volatile("s_waitcnt lgkmcnt(" #n ")" ::: "memory")
; #define PG8_BAR __builtin_amdgcn_s_barrier()
; #define PG8_SCHED __builtin_amdgcn_sched_barrier(0)
; template <class Epi, class Sched, bool ALIGN_EPI = false, bool SP2 = false>
; __device__ __forceinline__ void gemm_phase(PG8_LAS unsigned char* lds, const Gemm g, const Sched& S, const Epi& E) {
;     ...
;             PG8_WAIT_V(8); PG8_WAIT_L(0); PG8_BAR; PG8_MMA(1, 0, At, B0); PG8_MMA(1, 1, At, B1); PG8_BAR; PG8_SCHED;
;             PG8_LDB(B0, 1, 0); PG8_LDB(B1, 1, 1); PG8_SCHED; PG8_LDA(At, 1, 0); PG8_STAGE(PG8_SA(0, 1), a2 + hstep, voffA);
;             PG8_WAIT_V(8); PG8_WAIT_L(0); PG8_BAR; PG8_MMA(0, 0, At, B0); PG8_MMA(0, 1, At, B1); PG8_BAR; PG8_SCHED;
	s_setprio 1
	v_mfma_f32_16x16x32_bf16 v[62:65], v[146:149], v[188:191], v[62:65]
	v_mfma_f32_16x16x32_bf16 v[58:61], v[164:167], v[188:191], v[58:61]
	v_mfma_f32_16x16x32_bf16 v[46:49], v[146:149], v[196:199], v[46:49]
	v_mfma_f32_16x16x32_bf16 v[42:45], v[164:167], v[196:199], v[42:45]
	v_mfma_f32_16x16x32_bf16 v[30:33], v[146:149], v[204:207], v[30:33]
	v_mfma_f32_16x16x32_bf16 v[26:29], v[164:167], v[204:207], v[26:29]
	v_mfma_f32_16x16x32_bf16 v[14:17], v[146:149], v[214:217], v[14:17]
	v_mfma_f32_16x16x32_bf16 v[10:13], v[164:167], v[214:217], v[10:13]
	v_mfma_f32_16x16x32_bf16 v[62:65], v[160:163], v[192:195], v[62:65]
	v_mfma_f32_16x16x32_bf16 v[58:61], v[168:171], v[192:195], v[58:61]
	v_mfma_f32_16x16x32_bf16 v[46:49], v[160:163], v[200:203], v[46:49]
	v_mfma_f32_16x16x32_bf16 v[42:45], v[168:171], v[200:203], v[42:45]
	v_mfma_f32_16x16x32_bf16 v[30:33], v[160:163], v[210:213], v[30:33]
	v_mfma_f32_16x16x32_bf16 v[26:29], v[168:171], v[210:213], v[26:29]
	v_mfma_f32_16x16x32_bf16 v[14:17], v[160:163], v[218:221], v[14:17]
	v_mfma_f32_16x16x32_bf16 v[10:13], v[168:171], v[218:221], v[10:13]
	v_mfma_f32_16x16x32_bf16 v[54:57], v[172:175], v[188:191], v[54:57]
	v_mfma_f32_16x16x32_bf16 v[50:53], v[180:183], v[188:191], v[50:53]
	v_mfma_f32_16x16x32_bf16 v[38:41], v[172:175], v[196:199], v[38:41]
	v_mfma_f32_16x16x32_bf16 v[34:37], v[180:183], v[196:199], v[34:37]
	v_mfma_f32_16x16x32_bf16 v[22:25], v[172:175], v[204:207], v[22:25]
	v_mfma_f32_16x16x32_bf16 v[18:21], v[180:183], v[204:207], v[18:21]
	v_mfma_f32_16x16x32_bf16 v[6:9], v[172:175], v[214:217], v[6:9]
	v_mfma_f32_16x16x32_bf16 v[2:5], v[180:183], v[214:217], v[2:5]
	v_mfma_f32_16x16x32_bf16 v[54:57], v[176:179], v[192:195], v[54:57]
	v_mfma_f32_16x16x32_bf16 v[50:53], v[184:187], v[192:195], v[50:53]
	v_mfma_f32_16x16x32_bf16 v[38:41], v[176:179], v[200:203], v[38:41]
	v_mfma_f32_16x16x32_bf16 v[34:37], v[184:187], v[200:203], v[34:37]
	v_mfma_f32_16x16x32_bf16 v[22:25], v[176:179], v[210:213], v[22:25]
	v_mfma_f32_16x16x32_bf16 v[18:21], v[184:187], v[210:213], v[18:21]
	v_mfma_f32_16x16x32_bf16 v[6:9], v[176:179], v[218:221], v[6:9]
	v_mfma_f32_16x16x32_bf16 v[2:5], v[184:187], v[218:221], v[2:5]
	s_setprio 0
	s_barrier
	ds_read_b128 v[146:149], v157
	ds_read_b128 v[160:163], v157 offset:1024
	ds_read_b128 v[164:167], v157 offset:2048
	ds_read_b128 v[168:171], v157 offset:3072
	ds_read_b128 v[172:175], v158
	ds_read_b128 v[176:179], v158 offset:1024
	ds_read_b128 v[180:183], v158 offset:2048
	ds_read_b128 v[184:187], v158 offset:3072
	s_add_u32 s0, s28, 0x40000
	s_addc_u32 s1, s29, 0
	s_mov_b32 m0, s36
	v_lshl_add_u64 v[230:231], s[0:1], 0, v[130:131]
	ds_read_b128 v[188:191], v155 offset:32768
	ds_read_b128 v[192:195], v155 offset:33792
	ds_read_b128 v[196:199], v155 offset:34816
	ds_read_b128 v[200:203], v155 offset:35840
	ds_read_b128 v[204:207], v155 offset:36864
	ds_read_b128 v[210:213], v155 offset:37888
	ds_read_b128 v[214:217], v155 offset:38912
	ds_read_b128 v[218:221], v155 offset:39936
	global_load_lds_dwordx4 v[230:231], off
	v_lshl_add_u64 v[230:231], s[0:1], 0, v[134:135]
	s_mov_b32 m0, s37
	s_nop 0
	global_load_lds_dwordx4 v[230:231], off
	s_waitcnt vmcnt(8)
	s_waitcnt lgkmcnt(0)
	s_barrier
	s_setprio 1
	v_mfma_f32_16x16x32_bf16 v[126:129], v[146:149], v[188:191], v[126:129]
	v_mfma_f32_16x16x32_bf16 v[122:125], v[164:167], v[188:191], v[122:125]
	v_mfma_f32_16x16x32_bf16 v[110:113], v[146:149], v[196:199], v[110:113]
	v_mfma_f32_16x16x32_bf16 v[106:109], v[164:167], v[196:199], v[106:109]
	v_mfma_f32_16x16x32_bf16 v[94:97], v[146:149], v[204:207], v[94:97]
	v_mfma_f32_16x16x32_bf16 v[90:93], v[164:167], v[204:207], v[90:93]
	v_mfma_f32_16x16x32_bf16 v[78:81], v[146:149], v[214:217], v[78:81]
	v_mfma_f32_16x16x32_bf16 v[74:77], v[164:167], v[214:217], v[74:77]
	v_mfma_f32_16x16x32_bf16 v[126:129], v[160:163], v[192:195], v[126:129]
	v_mfma_f32_16x16x32_bf16 v[122:125], v[168:171], v[192:195], v[122:125]
	v_mfma_f32_16x16x32_bf16 v[110:113], v[160:163], v[200:203], v[110:113]
	v_mfma_f32_16x16x32_bf16 v[106:109], v[168:171], v[200:203], v[106:109]
	v_mfma_f32_16x16x32_bf16 v[94:97], v[160:163], v[210:213], v[94:97]
	v_mfma_f32_16x16x32_bf16 v[90:93], v[168:171], v[210:213], v[90:93]
	v_mfma_f32_16x16x32_bf16 v[78:81], v[160:163], v[218:221], v[78:81]
	v_mfma_f32_16x16x32_bf16 v[74:77], v[168:171], v[218:221], v[74:77]
	v_mfma_f32_16x16x32_bf16 v[118:121], v[172:175], v[188:191], v[118:121]
	v_mfma_f32_16x16x32_bf16 v[114:117], v[180:183], v[188:191], v[114:117]
	v_mfma_f32_16x16x32_bf16 v[102:105], v[172:175], v[196:199], v[102:105]
	v_mfma_f32_16x16x32_bf16 v[98:101], v[180:183], v[196:199], v[98:101]
	v_mfma_f32_16x16x32_bf16 v[86:89], v[172:175], v[204:207], v[86:89]
	v_mfma_f32_16x16x32_bf16 v[82:85], v[180:183], v[204:207], v[82:85]
	v_mfma_f32_16x16x32_bf16 v[70:73], v[172:175], v[214:217], v[70:73]
	v_mfma_f32_16x16x32_bf16 v[66:69], v[180:183], v[214:217], v[66:69]
	v_mfma_f32_16x16x32_bf16 v[118:121], v[176:179], v[192:195], v[118:121]
	v_mfma_f32_16x16x32_bf16 v[114:117], v[184:187], v[192:195], v[114:117]
	v_mfma_f32_16x16x32_bf16 v[102:105], v[176:179], v[200:203], v[102:105]
	v_mfma_f32_16x16x32_bf16 v[98:101], v[184:187], v[200:203], v[98:101]
	v_mfma_f32_16x16x32_bf16 v[86:89], v[176:179], v[210:213], v[86:89]
	v_mfma_f32_16x16x32_bf16 v[82:85], v[184:187], v[210:213], v[82:85]
	v_mfma_f32_16x16x32_bf16 v[70:73], v[176:179], v[218:221], v[70:73]
	v_mfma_f32_16x16x32_bf16 v[66:69], v[184:187], v[218:221], v[66:69]
	s_setprio 0
	s_barrier
; #define PG8_STAGE(bufoff, gbase, voff) do { _Pragma("unroll") for (int _i = 0; _i < 2; ++_i) \
;         __builtin_amdgcn_global_load_lds((const unsigned*)((const char*)(gbase) + (voff)[_i]), (PG8_LAS unsigned*)(lds + (bufoff) + ldsw + _i * 8192), 16, 0, 0); } while (0)
; #define PG8_LDA(dst, b, h) do { _Pragma("unroll") for (int m = 0; m < 4; ++m) _Pragma("unroll") for (int k = 0; k < 2; ++k) dst[m][k] = *(const PG8_LAS bf16x8*)(lds + PG8_SA(b, h) + aoff + m * 2048 + k * 1024); } while (0)
; #define PG8_MMA(ai, bj, At, Bt) do { __builtin_amdgcn_s_setprio(1); _Pragma("unroll") for (int m = 0; m < 4; ++m) _Pragma("unroll") for (int n = 0; n < 2; ++n) _Pragma("unroll") for (int k = 0; k < 2; ++k) \
;         acc[ai][bj][m][n] = __builtin_amdgcn_mfma_f32_16x16x32_bf16(Bt[n][k], At[m][k], acc[ai][bj][m][n], 0, 0, 0); __builtin_amdgcn_s_setprio(0); } while (0)
; #define PG8_WAIT_V(n) asm volatile("s_waitcnt vmcnt(" #n ")" ::: "memory")
; #define PG8_WAIT_L(n) asm volatile("s_waitcnt lgkmcnt(" #n ")" ::: "memory")
; #define PG8_BAR __builtin_amdgcn_s_barrier()
; #define PG8_SCHED __builtin_amdgcn_sched_barrier(0)
; template <class Epi, class Sched, bool ALIGN_EPI = false, bool SP2 = false>
; __device__ __forceinline__ void gemm_phase(PG8_LAS unsigned char* lds, const Gemm g, const Sched& S, const Epi& E) {
;     ...
;             PG8_LDA(At, 1, 1); PG8_STAGE(PG8_SB(1, 0), b3, voffB); PG8_STAGE(PG8_SB(1, 1), b3 + hstep, voffB); PG8_STAGE(PG8_SA(1, 0), a3, voffA);
;             PG8_WAIT_V(8); PG8_WAIT_L(0); PG8_BAR; PG8_MMA(1, 0, At, B0); PG8_MMA(1, 1, At, B1); PG8_BAR; PG8_SCHED;
	s_add_i32 s0, s45, s31
	v_lshl_add_u64 v[222:223], v[222:223], 0, s[10:11]
	s_mov_b32 m0, s0
	ds_read_b128 v[188:191], v155 offset:49152
	ds_read_b128 v[192:195], v155 offset:50176
	ds_read_b128 v[196:199], v155 offset:51200
	ds_read_b128 v[200:203], v155 offset:52224
	ds_read_b128 v[204:207], v155 offset:53248
	ds_read_b128 v[210:213], v155 offset:54272
	ds_read_b128 v[214:217], v155 offset:55296
	ds_read_b128 v[218:221], v155 offset:56320
	global_load_lds_dwordx4 v[222:223], off
	s_add_i32 m0, s0, 0x2000
	s_add_u32 s0, s26, 0x40080
	v_lshl_add_u64 v[222:223], v[224:225], 0, s[10:11]
	s_addc_u32 s1, s27, 0
	s_add_i32 s26, s46, s31
	global_load_lds_dwordx4 v[222:223], off
	v_lshl_add_u64 v[222:223], s[0:1], 0, v[132:133]
	s_mov_b32 m0, s26
	s_nop 0
	global_load_lds_dwordx4 v[222:223], off
	v_lshl_add_u64 v[222:223], s[0:1], 0, v[136:137]
	s_add_i32 m0, s26, 0x2000
	s_nop 0
	global_load_lds_dwordx4 v[222:223], off
	v_lshl_add_u64 v[222:223], v[226:227], 0, s[10:11]
	s_mov_b32 m0, s38
	s_nop 0
	global_load_lds_dwordx4 v[222:223], off
	v_lshl_add_u64 v[222:223], v[228:229], 0, s[10:11]
	s_mov_b32 m0, s39
	s_nop 0
	global_load_lds_dwordx4 v[222:223], off
	s_waitcnt vmcnt(8)
	s_waitcnt lgkmcnt(0)
	s_barrier
	s_setprio 1
	v_mfma_f32_16x16x32_bf16 v[62:65], v[146:149], v[188:191], v[62:65]
	v_mfma_f32_16x16x32_bf16 v[58:61], v[164:167], v[188:191], v[58:61]
	v_mfma_f32_16x16x32_bf16 v[46:49], v[146:149], v[196:199], v[46:49]
	v_mfma_f32_16x16x32_bf16 v[42:45], v[164:167], v[196:199], v[42:45]
	v_mfma_f32_16x16x32_bf16 v[30:33], v[146:149], v[204:207], v[30:33]
	v_mfma_f32_16x16x32_bf16 v[26:29], v[164:167], v[204:207], v[26:29]
	v_mfma_f32_16x16x32_bf16 v[14:17], v[146:149], v[214:217], v[14:17]
	v_mfma_f32_16x16x32_bf16 v[10:13], v[164:167], v[214:217], v[10:13]
	v_mfma_f32_16x16x32_bf16 v[62:65], v[160:163], v[192:195], v[62:65]
	v_mfma_f32_16x16x32_bf16 v[58:61], v[168:171], v[192:195], v[58:61]
	v_mfma_f32_16x16x32_bf16 v[46:49], v[160:163], v[200:203], v[46:49]
	v_mfma_f32_16x16x32_bf16 v[42:45], v[168:171], v[200:203], v[42:45]
	v_mfma_f32_16x16x32_bf16 v[30:33], v[160:163], v[210:213], v[30:33]
	v_mfma_f32_16x16x32_bf16 v[26:29], v[168:171], v[210:213], v[26:29]
	v_mfma_f32_16x16x32_bf16 v[14:17], v[160:163], v[218:221], v[14:17]
	v_mfma_f32_16x16x32_bf16 v[10:13], v[168:171], v[218:221], v[10:13]
	v_mfma_f32_16x16x32_bf16 v[54:57], v[172:175], v[188:191], v[54:57]
	v_mfma_f32_16x16x32_bf16 v[50:53], v[180:183], v[188:191], v[50:53]
	v_mfma_f32_16x16x32_bf16 v[38:41], v[172:175], v[196:199], v[38:41]
	v_mfma_f32_16x16x32_bf16 v[34:37], v[180:183], v[196:199], v[34:37]
	v_mfma_f32_16x16x32_bf16 v[22:25], v[172:175], v[204:207], v[22:25]
	v_mfma_f32_16x16x32_bf16 v[18:21], v[180:183], v[204:207], v[18:21]
	v_mfma_f32_16x16x32_bf16 v[6:9], v[172:175], v[214:217], v[6:9]
	v_mfma_f32_16x16x32_bf16 v[2:5], v[180:183], v[214:217], v[2:5]
	v_mfma_f32_16x16x32_bf16 v[54:57], v[176:179], v[192:195], v[54:57]
	v_mfma_f32_16x16x32_bf16 v[50:53], v[184:187], v[192:195], v[50:53]
	v_mfma_f32_16x16x32_bf16 v[38:41], v[176:179], v[200:203], v[38:41]
	v_mfma_f32_16x16x32_bf16 v[34:37], v[184:187], v[200:203], v[34:37]
	v_mfma_f32_16x16x32_bf16 v[22:25], v[176:179], v[210:213], v[22:25]
	v_mfma_f32_16x16x32_bf16 v[18:21], v[184:187], v[210:213], v[18:21]
	v_mfma_f32_16x16x32_bf16 v[6:9], v[176:179], v[218:221], v[6:9]
	v_mfma_f32_16x16x32_bf16 v[2:5], v[184:187], v[218:221], v[2:5]
	s_setprio 0
	s_barrier
	s_add_i32 s54, s54, 2
	s_add_u32 s4, s4, 0x100
	s_addc_u32 s5, s5, 0
	s_add_u32 s52, s52, 0x100
	s_addc_u32 s53, s53, 0
	s_cmp_gt_u32 s54, 13
	s_cbranch_scc0 .LBB0_1380
	s_and_b64 vcc, exec, s[12:13]
	s_cbranch_vccz .LBB0_1383
	s_barrier

; #define PG8_STAGE(bufoff, gbase, voff) do { _Pragma("unroll") for (int _i = 0; _i < 2; ++_i) \
;         __builtin_amdgcn_global_load_lds((const unsigned*)((const char*)(gbase) + (voff)[_i]), (PG8_LAS unsigned*)(lds + (bufoff) + ldsw + _i * 8192), 16, 0, 0); } while (0)
; #define PG8_LDA(dst, b, h) do { _Pragma("unroll") for (int m = 0; m < 4; ++m) _Pragma("unroll") for (int k = 0; k < 2; ++k) dst[m][k] = *(const PG8_LAS bf16x8*)(lds + PG8_SA(b, h) + aoff + m * 2048 + k * 1024); } while (0)
; #define PG8_LDB(dst, b, h) do { _Pragma("unroll") for (int n = 0; n < 2; ++n) _Pragma("unroll") for (int k = 0; k < 2; ++k) dst[n][k] = *(const PG8_LAS bf16x8*)(lds + PG8_SB(b, h) + boff + n * 2048 + k * 1024); } while (0)
; #define PG8_MMA(ai, bj, At, Bt) do { __builtin_amdgcn_s_setprio(1); _Pragma("unroll") for (int m = 0; m < 4; ++m) _Pragma("unroll") for (int n = 0; n < 2; ++n) _Pragma("unroll") for (int k = 0; k < 2; ++k) \
;         acc[ai][bj][m][n] = __builtin_amdgcn_mfma_f32_16x16x32_bf16(Bt[n][k], At[m][k], acc[ai][bj][m][n], 0, 0, 0); __builtin_amdgcn_s_setprio(0); } while (0)
; #define PG8_WAIT_V(n) asm volatile("s_waitcnt vmcnt(" #n ")" ::: "memory")
; #define PG8_WAIT_L(n) asm volatile("s_waitcnt lgkmcnt(" #n ")" ::: "memory")
; #define PG8_BAR __builtin_amdgcn_s_barrier()
; #define PG8_SCHED __builtin_amdgcn_sched_barrier(0)
; template <class Epi, class Sched, bool ALIGN_EPI = false, bool SP2 = false>
; __device__ __forceinline__ void gemm_phase(PG8_LAS unsigned char* lds, const Gemm g, const Sched& S, const Epi& E) {
;     ...
;             PG8_LDB(B0, 0, 0); PG8_LDB(B1, 0, 1); PG8_SCHED; PG8_LDA(At, 0, 0); PG8_STAGE(PG8_SA(1, 1), a1 + hstep, voffA);
;             PG8_WAIT_V(8); PG8_WAIT_L(0); PG8_BAR; PG8_MMA(0, 0, At, B0); PG8_MMA(0, 1, At, B1); PG8_BAR; PG8_SCHED;
;             PG8_LDA(At, 0, 1); PG8_STAGE(PG8_SB(0, 0), b2, voffB); PG8_STAGE(PG8_SB(0, 1), b2 + hstep, voffB); PG8_STAGE(PG8_SA(0, 0), a2, voffA);
;             PG8_WAIT_V(8); PG8_WAIT_L(0); PG8_BAR; PG8_MMA(1, 0, At, B0); PG8_MMA(1, 1, At, B1); PG8_BAR; PG8_SCHED;
.LBB0_1498:
	ds_read_b128 v[142:145], v148
	ds_read_b128 v[154:157], v148 offset:1024
	ds_read_b128 v[158:161], v148 offset:2048
	ds_read_b128 v[162:165], v148 offset:3072
	ds_read_b128 v[166:169], v149
	ds_read_b128 v[170:173], v149 offset:1024
	ds_read_b128 v[174:177], v149 offset:2048
	ds_read_b128 v[178:181], v149 offset:3072
	s_add_u32 s24, s22, 0x4000
	s_addc_u32 s25, s23, 0
	s_cmp_eq_u32 s47, 60
	s_cselect_b32 s27, s11, s25
	s_cselect_b32 s26, s43, s24
	s_cselect_b32 s25, s9, s46
	s_cselect_b32 s24, s44, s45
	v_lshl_add_u64 v[214:215], s[22:23], 0, v[136:137]
	s_add_i32 m0, s19, 0xc000
	ds_read_b128 v[182:185], v150
	ds_read_b128 v[186:189], v150 offset:1024
	ds_read_b128 v[190:193], v150 offset:2048
	ds_read_b128 v[194:197], v150 offset:3072
	ds_read_b128 v[198:201], v150 offset:4096
	ds_read_b128 v[202:205], v150 offset:5120
	ds_read_b128 v[206:209], v150 offset:6144
	ds_read_b128 v[210:213], v150 offset:7168
	global_load_lds_dwordx4 v[214:215], off
	v_lshl_add_u64 v[214:215], s[22:23], 0, v[138:139]
	s_add_i32 m0, s19, 0xe000
	s_nop 0
	global_load_lds_dwordx4 v[214:215], off
	s_waitcnt vmcnt(8)
	s_waitcnt lgkmcnt(0)
	s_barrier
	s_setprio 1
	v_mfma_f32_16x16x32_bf16 v[124:127], v[142:145], v[182:185], v[124:127]
	v_mfma_f32_16x16x32_bf16 v[120:123], v[158:161], v[182:185], v[120:123]
	v_mfma_f32_16x16x32_bf16 v[108:111], v[142:145], v[190:193], v[108:111]
	v_mfma_f32_16x16x32_bf16 v[104:107], v[158:161], v[190:193], v[104:107]
	v_mfma_f32_16x16x32_bf16 v[92:95], v[142:145], v[198:201], v[92:95]
	v_mfma_f32_16x16x32_bf16 v[88:91], v[158:161], v[198:201], v[88:91]
	v_mfma_f32_16x16x32_bf16 v[76:79], v[142:145], v[206:209], v[76:79]
	v_mfma_f32_16x16x32_bf16 v[72:75], v[158:161], v[206:209], v[72:75]
	v_mfma_f32_16x16x32_bf16 v[124:127], v[154:157], v[186:189], v[124:127]
	v_mfma_f32_16x16x32_bf16 v[120:123], v[162:165], v[186:189], v[120:123]
	v_mfma_f32_16x16x32_bf16 v[108:111], v[154:157], v[194:197], v[108:111]
	v_mfma_f32_16x16x32_bf16 v[104:107], v[162:165], v[194:197], v[104:107]
	v_mfma_f32_16x16x32_bf16 v[92:95], v[154:157], v[202:205], v[92:95]
	v_mfma_f32_16x16x32_bf16 v[88:91], v[162:165], v[202:205], v[88:91]
	v_mfma_f32_16x16x32_bf16 v[76:79], v[154:157], v[210:213], v[76:79]
	v_mfma_f32_16x16x32_bf16 v[72:75], v[162:165], v[210:213], v[72:75]
	v_mfma_f32_16x16x32_bf16 v[116:119], v[166:169], v[182:185], v[116:119]
	v_mfma_f32_16x16x32_bf16 v[112:115], v[174:177], v[182:185], v[112:115]
	v_mfma_f32_16x16x32_bf16 v[100:103], v[166:169], v[190:193], v[100:103]
	v_mfma_f32_16x16x32_bf16 v[96:99], v[174:177], v[190:193], v[96:99]
	v_mfma_f32_16x16x32_bf16 v[84:87], v[166:169], v[198:201], v[84:87]
	v_mfma_f32_16x16x32_bf16 v[80:83], v[174:177], v[198:201], v[80:83]
	v_mfma_f32_16x16x32_bf16 v[68:71], v[166:169], v[206:209], v[68:71]
	v_mfma_f32_16x16x32_bf16 v[64:67], v[174:177], v[206:209], v[64:67]
	v_mfma_f32_16x16x32_bf16 v[116:119], v[170:173], v[186:189], v[116:119]
	v_mfma_f32_16x16x32_bf16 v[112:115], v[178:181], v[186:189], v[112:115]
	v_mfma_f32_16x16x32_bf16 v[100:103], v[170:173], v[194:197], v[100:103]
	v_mfma_f32_16x16x32_bf16 v[96:99], v[178:181], v[194:197], v[96:99]
	v_mfma_f32_16x16x32_bf16 v[84:87], v[170:173], v[202:205], v[84:87]
	v_mfma_f32_16x16x32_bf16 v[80:83], v[178:181], v[202:205], v[80:83]
	v_mfma_f32_16x16x32_bf16 v[68:71], v[170:173], v[210:213], v[68:71]
	v_mfma_f32_16x16x32_bf16 v[64:67], v[178:181], v[210:213], v[64:67]
	s_setprio 0
	s_barrier
	s_add_i32 s48, s37, s29
	v_lshl_add_u64 v[214:215], s[24:25], 0, v[130:131]
	s_mov_b32 m0, s48
	ds_read_b128 v[182:185], v150 offset:16384
	ds_read_b128 v[186:189], v150 offset:17408
	ds_read_b128 v[190:193], v150 offset:18432
	ds_read_b128 v[194:197], v150 offset:19456
	ds_read_b128 v[198:201], v150 offset:20480
	ds_read_b128 v[202:205], v150 offset:21504
	ds_read_b128 v[206:209], v150 offset:22528
	ds_read_b128 v[210:213], v150 offset:23552
	global_load_lds_dwordx4 v[214:215], off
	s_add_i32 m0, s48, 0x2000
	s_add_u32 s48, s24, 0x100000
	v_lshl_add_u64 v[216:217], s[24:25], 0, v[134:135]
	s_addc_u32 s49, s25, 0
	s_add_i32 s52, s38, s29
	global_load_lds_dwordx4 v[216:217], off
	v_lshl_add_u64 v[218:219], s[48:49], 0, v[130:131]
	s_mov_b32 m0, s52
	v_lshl_add_u64 v[220:221], s[26:27], 0, v[132:133]
	global_load_lds_dwordx4 v[218:219], off
	v_lshl_add_u64 v[218:219], s[48:49], 0, v[134:135]
	s_add_i32 m0, s52, 0x2000
	s_nop 0
	global_load_lds_dwordx4 v[218:219], off
	v_lshl_add_u64 v[218:219], s[26:27], 0, v[128:129]
	s_mov_b32 m0, s19
	s_nop 0
	global_load_lds_dwordx4 v[218:219], off
	s_mov_b32 m0, s21
	s_nop 0
	global_load_lds_dwordx4 v[220:221], off
	s_waitcnt vmcnt(8)
	s_waitcnt lgkmcnt(0)
	s_barrier
; #define PG8_STAGE(bufoff, gbase, voff) do { _Pragma("unroll") for (int _i = 0; _i < 2; ++_i) \
;         __builtin_amdgcn_global_load_lds((const unsigned*)((const char*)(gbase) + (voff)[_i]), (PG8_LAS unsigned*)(lds + (bufoff) + ldsw + _i * 8192), 16, 0, 0); } while (0)
; #define PG8_LDA(dst, b, h) do { _Pragma("unroll") for (int m = 0; m < 4; ++m) _Pragma("unroll") for (int k = 0; k < 2; ++k) dst[m][k] = *(const PG8_LAS bf16x8*)(lds + PG8_SA(b, h) + aoff + m * 2048 + k * 1024); } while (0)
; #define PG8_LDB(dst, b, h) do { _Pragma("unroll") for (int n = 0; n < 2; ++n) _Pragma("unroll") for (int k = 0; k < 2; ++k) dst[n][k] = *(const PG8_LAS bf16x8*)(lds + PG8_SB(b, h) + boff + n * 2048 + k * 1024); } while (0)
; #define PG8_MMA(ai, bj, At, Bt) do { __builtin_amdgcn_s_setprio(1); _Pragma("unroll") for (int m = 0; m < 4; ++m) _Pragma("unroll") for (int n = 0; n < 2; ++n) _Pragma("unroll") for (int k = 0; k < 2; ++k) \
;         acc[ai][bj][m][n] = __builtin_amdgcn_mfma_f32_16x16x32_bf16(Bt[n][k], At[m][k], acc[ai][bj][m][n], 0, 0, 0); __builtin_amdgcn_s_setprio(0); } while (0)
; #define PG8_WAIT_V(n) asm volatile("s_waitcnt vmcnt(" #n ")" ::: "memory")
; #define PG8_WAIT_L(n) asm volatile("s_waitcnt lgkmcnt(" #n ")" ::: "memory")
; #define PG8_BAR __builtin_amdgcn_s_barrier()
; #define PG8_SCHED __builtin_amdgcn_sched_barrier(0)
; template <class Epi, class Sched, bool ALIGN_EPI = false, bool SP2 = false>
; __device__ __forceinline__ void gemm_phase(PG8_LAS unsigned char* lds, const Gemm g, const Sched& S, const Epi& E) {
;     ...
;             PG8_WAIT_V(8); PG8_WAIT_L(0); PG8_BAR; PG8_MMA(1, 0, At, B0); PG8_MMA(1, 1, At, B1); PG8_BAR; PG8_SCHED;
;             PG8_LDB(B0, 1, 0); PG8_LDB(B1, 1, 1); PG8_SCHED; PG8_LDA(At, 1, 0); PG8_STAGE(PG8_SA(0, 1), a2 + hstep, voffA);
;             PG8_WAIT_V(8); PG8_WAIT_L(0); PG8_BAR; PG8_MMA(0, 0, At, B0); PG8_MMA(0, 1, At, B1); PG8_BAR; PG8_SCHED;
	s_setprio 1
	v_mfma_f32_16x16x32_bf16 v[60:63], v[142:145], v[182:185], v[60:63]
	v_mfma_f32_16x16x32_bf16 v[56:59], v[158:161], v[182:185], v[56:59]
	v_mfma_f32_16x16x32_bf16 v[44:47], v[142:145], v[190:193], v[44:47]
	v_mfma_f32_16x16x32_bf16 v[40:43], v[158:161], v[190:193], v[40:43]
	v_mfma_f32_16x16x32_bf16 v[28:31], v[142:145], v[198:201], v[28:31]
	v_mfma_f32_16x16x32_bf16 v[24:27], v[158:161], v[198:201], v[24:27]
	v_mfma_f32_16x16x32_bf16 v[12:15], v[142:145], v[206:209], v[12:15]
	v_mfma_f32_16x16x32_bf16 v[8:11], v[158:161], v[206:209], v[8:11]
	v_mfma_f32_16x16x32_bf16 v[60:63], v[154:157], v[186:189], v[60:63]
	v_mfma_f32_16x16x32_bf16 v[56:59], v[162:165], v[186:189], v[56:59]
	v_mfma_f32_16x16x32_bf16 v[44:47], v[154:157], v[194:197], v[44:47]
	v_mfma_f32_16x16x32_bf16 v[40:43], v[162:165], v[194:197], v[40:43]
	v_mfma_f32_16x16x32_bf16 v[28:31], v[154:157], v[202:205], v[28:31]
	v_mfma_f32_16x16x32_bf16 v[24:27], v[162:165], v[202:205], v[24:27]
	v_mfma_f32_16x16x32_bf16 v[12:15], v[154:157], v[210:213], v[12:15]
	v_mfma_f32_16x16x32_bf16 v[8:11], v[162:165], v[210:213], v[8:11]
	v_mfma_f32_16x16x32_bf16 v[52:55], v[166:169], v[182:185], v[52:55]
	v_mfma_f32_16x16x32_bf16 v[48:51], v[174:177], v[182:185], v[48:51]
	v_mfma_f32_16x16x32_bf16 v[36:39], v[166:169], v[190:193], v[36:39]
	v_mfma_f32_16x16x32_bf16 v[32:35], v[174:177], v[190:193], v[32:35]
	v_mfma_f32_16x16x32_bf16 v[20:23], v[166:169], v[198:201], v[20:23]
	v_mfma_f32_16x16x32_bf16 v[16:19], v[174:177], v[198:201], v[16:19]
	v_mfma_f32_16x16x32_bf16 v[4:7], v[166:169], v[206:209], v[4:7]
	v_mfma_f32_16x16x32_bf16 v[0:3], v[174:177], v[206:209], v[0:3]
	v_mfma_f32_16x16x32_bf16 v[52:55], v[170:173], v[186:189], v[52:55]
	v_mfma_f32_16x16x32_bf16 v[48:51], v[178:181], v[186:189], v[48:51]
	v_mfma_f32_16x16x32_bf16 v[36:39], v[170:173], v[194:197], v[36:39]
	v_mfma_f32_16x16x32_bf16 v[32:35], v[178:181], v[194:197], v[32:35]
	v_mfma_f32_16x16x32_bf16 v[20:23], v[170:173], v[202:205], v[20:23]
	v_mfma_f32_16x16x32_bf16 v[16:19], v[178:181], v[202:205], v[16:19]
	v_mfma_f32_16x16x32_bf16 v[4:7], v[170:173], v[210:213], v[4:7]
	v_mfma_f32_16x16x32_bf16 v[0:3], v[178:181], v[210:213], v[0:3]
	s_setprio 0
	s_barrier
	ds_read_b128 v[142:145], v151
	ds_read_b128 v[154:157], v151 offset:1024
	ds_read_b128 v[158:161], v151 offset:2048
	ds_read_b128 v[162:165], v151 offset:3072
	ds_read_b128 v[166:169], v152
	ds_read_b128 v[170:173], v152 offset:1024
	ds_read_b128 v[174:177], v152 offset:2048
	ds_read_b128 v[178:181], v152 offset:3072
	s_add_u32 s26, s26, 0x4000
	s_addc_u32 s27, s27, 0
	s_mov_b32 m0, s31
	v_lshl_add_u64 v[222:223], s[26:27], 0, v[128:129]
	ds_read_b128 v[182:185], v150 offset:32768
	ds_read_b128 v[186:189], v150 offset:33792
	ds_read_b128 v[190:193], v150 offset:34816
	ds_read_b128 v[194:197], v150 offset:35840
	ds_read_b128 v[198:201], v150 offset:36864
	ds_read_b128 v[202:205], v150 offset:37888
	ds_read_b128 v[206:209], v150 offset:38912
	ds_read_b128 v[210:213], v150 offset:39936
	global_load_lds_dwordx4 v[222:223], off
	v_lshl_add_u64 v[222:223], s[26:27], 0, v[132:133]
	s_mov_b32 m0, s33
	s_nop 0
	global_load_lds_dwordx4 v[222:223], off
	s_waitcnt vmcnt(8)
	s_waitcnt lgkmcnt(0)
	s_barrier
	s_setprio 1
	v_mfma_f32_16x16x32_bf16 v[124:127], v[142:145], v[182:185], v[124:127]
	v_mfma_f32_16x16x32_bf16 v[120:123], v[158:161], v[182:185], v[120:123]
	v_mfma_f32_16x16x32_bf16 v[108:111], v[142:145], v[190:193], v[108:111]
	v_mfma_f32_16x16x32_bf16 v[104:107], v[158:161], v[190:193], v[104:107]
	v_mfma_f32_16x16x32_bf16 v[92:95], v[142:145], v[198:201], v[92:95]
	v_mfma_f32_16x16x32_bf16 v[88:91], v[158:161], v[198:201], v[88:91]
	v_mfma_f32_16x16x32_bf16 v[76:79], v[142:145], v[206:209], v[76:79]
	v_mfma_f32_16x16x32_bf16 v[72:75], v[158:161], v[206:209], v[72:75]
	v_mfma_f32_16x16x32_bf16 v[124:127], v[154:157], v[186:189], v[124:127]
	v_mfma_f32_16x16x32_bf16 v[120:123], v[162:165], v[186:189], v[120:123]
	v_mfma_f32_16x16x32_bf16 v[108:111], v[154:157], v[194:197], v[108:111]
	v_mfma_f32_16x16x32_bf16 v[104:107], v[162:165], v[194:197], v[104:107]
	v_mfma_f32_16x16x32_bf16 v[92:95], v[154:157], v[202:205], v[92:95]
	v_mfma_f32_16x16x32_bf16 v[88:91], v[162:165], v[202:205], v[88:91]
	v_mfma_f32_16x16x32_bf16 v[76:79], v[154:157], v[210:213], v[76:79]
	v_mfma_f32_16x16x32_bf16 v[72:75], v[162:165], v[210:213], v[72:75]
	v_mfma_f32_16x16x32_bf16 v[116:119], v[166:169], v[182:185], v[116:119]
	v_mfma_f32_16x16x32_bf16 v[112:115], v[174:177], v[182:185], v[112:115]
	v_mfma_f32_16x16x32_bf16 v[100:103], v[166:169], v[190:193], v[100:103]
	v_mfma_f32_16x16x32_bf16 v[96:99], v[174:177], v[190:193], v[96:99]
	v_mfma_f32_16x16x32_bf16 v[84:87], v[166:169], v[198:201], v[84:87]
	v_mfma_f32_16x16x32_bf16 v[80:83], v[174:177], v[198:201], v[80:83]
	v_mfma_f32_16x16x32_bf16 v[68:71], v[166:169], v[206:209], v[68:71]
	v_mfma_f32_16x16x32_bf16 v[64:67], v[174:177], v[206:209], v[64:67]
	v_mfma_f32_16x16x32_bf16 v[116:119], v[170:173], v[186:189], v[116:119]
	v_mfma_f32_16x16x32_bf16 v[112:115], v[178:181], v[186:189], v[112:115]
	v_mfma_f32_16x16x32_bf16 v[100:103], v[170:173], v[194:197], v[100:103]
	v_mfma_f32_16x16x32_bf16 v[96:99], v[178:181], v[194:197], v[96:99]
	v_mfma_f32_16x16x32_bf16 v[84:87], v[170:173], v[202:205], v[84:87]
	v_mfma_f32_16x16x32_bf16 v[80:83], v[178:181], v[202:205], v[80:83]
	v_mfma_f32_16x16x32_bf16 v[68:71], v[170:173], v[210:213], v[68:71]
	v_mfma_f32_16x16x32_bf16 v[64:67], v[178:181], v[210:213], v[64:67]
	s_setprio 0
	s_barrier
; #define PG8_STAGE(bufoff, gbase, voff) do { _Pragma("unroll") for (int _i = 0; _i < 2; ++_i) \
;         __builtin_amdgcn_global_load_lds((const unsigned*)((const char*)(gbase) + (voff)[_i]), (PG8_LAS unsigned*)(lds + (bufoff) + ldsw + _i * 8192), 16, 0, 0); } while (0)
; #define PG8_LDA(dst, b, h) do { _Pragma("unroll") for (int m = 0; m < 4; ++m) _Pragma("unroll") for (int k = 0; k < 2; ++k) dst[m][k] = *(const PG8_LAS bf16x8*)(lds + PG8_SA(b, h) + aoff + m * 2048 + k * 1024); } while (0)
; #define PG8_MMA(ai, bj, At, Bt) do { __builtin_amdgcn_s_setprio(1); _Pragma("unroll") for (int m = 0; m < 4; ++m) _Pragma("unroll") for (int n = 0; n < 2; ++n) _Pragma("unroll") for (int k = 0; k < 2; ++k) \
;         acc[ai][bj][m][n] = __builtin_amdgcn_mfma_f32_16x16x32_bf16(Bt[n][k], At[m][k], acc[ai][bj][m][n], 0, 0, 0); __builtin_amdgcn_s_setprio(0); } while (0)
; #define PG8_WAIT_V(n) asm volatile("s_waitcnt vmcnt(" #n ")" ::: "memory")
; #define PG8_WAIT_L(n) asm volatile("s_waitcnt lgkmcnt(" #n ")" ::: "memory")
; #define PG8_BAR __builtin_amdgcn_s_barrier()
; #define PG8_SCHED __builtin_amdgcn_sched_barrier(0)
; template <class Epi, class Sched, bool ALIGN_EPI = false, bool SP2 = false>
; __device__ __forceinline__ void gemm_phase(PG8_LAS unsigned char* lds, const Gemm g, const Sched& S, const Epi& E) {
;     ...
;             PG8_LDA(At, 1, 1); PG8_STAGE(PG8_SB(1, 0), b3, voffB); PG8_STAGE(PG8_SB(1, 1), b3 + hstep, voffB); PG8_STAGE(PG8_SA(1, 0), a3, voffA);
;             PG8_WAIT_V(8); PG8_WAIT_L(0); PG8_BAR; PG8_MMA(1, 0, At, B0); PG8_MMA(1, 1, At, B1); PG8_BAR; PG8_SCHED;
	s_add_i32 s26, s39, s29
	v_lshl_add_u64 v[214:215], v[214:215], 0, s[4:5]
	s_mov_b32 m0, s26
	ds_read_b128 v[182:185], v150 offset:49152
	ds_read_b128 v[186:189], v150 offset:50176
	ds_read_b128 v[190:193], v150 offset:51200
	ds_read_b128 v[194:197], v150 offset:52224
	ds_read_b128 v[198:201], v150 offset:53248
	ds_read_b128 v[202:205], v150 offset:54272
	ds_read_b128 v[206:209], v150 offset:55296
	ds_read_b128 v[210:213], v150 offset:56320
	global_load_lds_dwordx4 v[214:215], off
	s_add_i32 m0, s26, 0x2000
	s_add_u32 s24, s24, 0x100080
	v_lshl_add_u64 v[214:215], v[216:217], 0, s[4:5]
	s_addc_u32 s25, s25, 0
	s_add_i32 s26, s40, s29
	global_load_lds_dwordx4 v[214:215], off
	v_lshl_add_u64 v[214:215], s[24:25], 0, v[130:131]
	s_mov_b32 m0, s26
	s_nop 0
	global_load_lds_dwordx4 v[214:215], off
	v_lshl_add_u64 v[214:215], s[24:25], 0, v[134:135]
	s_add_i32 m0, s26, 0x2000
	s_nop 0
	global_load_lds_dwordx4 v[214:215], off
	v_lshl_add_u64 v[214:215], v[218:219], 0, s[70:71]
	s_mov_b32 m0, s34
	s_nop 0
	global_load_lds_dwordx4 v[214:215], off
	v_lshl_add_u64 v[214:215], v[220:221], 0, s[70:71]
	s_mov_b32 m0, s35
	s_nop 0
	global_load_lds_dwordx4 v[214:215], off
	s_waitcnt vmcnt(8)
	s_waitcnt lgkmcnt(0)
	s_barrier
	s_setprio 1
	v_mfma_f32_16x16x32_bf16 v[60:63], v[142:145], v[182:185], v[60:63]
	v_mfma_f32_16x16x32_bf16 v[56:59], v[158:161], v[182:185], v[56:59]
	v_mfma_f32_16x16x32_bf16 v[44:47], v[142:145], v[190:193], v[44:47]
	v_mfma_f32_16x16x32_bf16 v[40:43], v[158:161], v[190:193], v[40:43]
	v_mfma_f32_16x16x32_bf16 v[28:31], v[142:145], v[198:201], v[28:31]
	v_mfma_f32_16x16x32_bf16 v[24:27], v[158:161], v[198:201], v[24:27]
	v_mfma_f32_16x16x32_bf16 v[12:15], v[142:145], v[206:209], v[12:15]
	v_mfma_f32_16x16x32_bf16 v[8:11], v[158:161], v[206:209], v[8:11]
	v_mfma_f32_16x16x32_bf16 v[60:63], v[154:157], v[186:189], v[60:63]
	v_mfma_f32_16x16x32_bf16 v[56:59], v[162:165], v[186:189], v[56:59]
	v_mfma_f32_16x16x32_bf16 v[44:47], v[154:157], v[194:197], v[44:47]
	v_mfma_f32_16x16x32_bf16 v[40:43], v[162:165], v[194:197], v[40:43]
	v_mfma_f32_16x16x32_bf16 v[28:31], v[154:157], v[202:205], v[28:31]
	v_mfma_f32_16x16x32_bf16 v[24:27], v[162:165], v[202:205], v[24:27]
	v_mfma_f32_16x16x32_bf16 v[12:15], v[154:157], v[210:213], v[12:15]
	v_mfma_f32_16x16x32_bf16 v[8:11], v[162:165], v[210:213], v[8:11]
	v_mfma_f32_16x16x32_bf16 v[52:55], v[166:169], v[182:185], v[52:55]
	v_mfma_f32_16x16x32_bf16 v[48:51], v[174:177], v[182:185], v[48:51]
	v_mfma_f32_16x16x32_bf16 v[36:39], v[166:169], v[190:193], v[36:39]
	v_mfma_f32_16x16x32_bf16 v[32:35], v[174:177], v[190:193], v[32:35]
	v_mfma_f32_16x16x32_bf16 v[20:23], v[166:169], v[198:201], v[20:23]
	v_mfma_f32_16x16x32_bf16 v[16:19], v[174:177], v[198:201], v[16:19]
	v_mfma_f32_16x16x32_bf16 v[4:7], v[166:169], v[206:209], v[4:7]
	v_mfma_f32_16x16x32_bf16 v[0:3], v[174:177], v[206:209], v[0:3]
	v_mfma_f32_16x16x32_bf16 v[52:55], v[170:173], v[186:189], v[52:55]
	v_mfma_f32_16x16x32_bf16 v[48:51], v[178:181], v[186:189], v[48:51]
	v_mfma_f32_16x16x32_bf16 v[36:39], v[170:173], v[194:197], v[36:39]
	v_mfma_f32_16x16x32_bf16 v[32:35], v[178:181], v[194:197], v[32:35]
	v_mfma_f32_16x16x32_bf16 v[20:23], v[170:173], v[202:205], v[20:23]
	v_mfma_f32_16x16x32_bf16 v[16:19], v[178:181], v[202:205], v[16:19]
	v_mfma_f32_16x16x32_bf16 v[4:7], v[170:173], v[210:213], v[4:7]
	v_mfma_f32_16x16x32_bf16 v[0:3], v[178:181], v[210:213], v[0:3]
	s_setprio 0
	s_barrier
	s_add_i32 s47, s47, 2
	s_add_u32 s22, s22, 0x10000
	s_addc_u32 s23, s23, 0
	s_add_u32 s45, s45, 0x100
	s_addc_u32 s46, s46, 0
	s_cmp_gt_u32 s47, 61
	s_cbranch_scc0 .LBB0_1498
	s_and_b64 vcc, exec, s[6:7]
	s_cbranch_vccz .LBB0_1501
	s_barrier
